# swiglu GEMM: row sums staged to LDS in the peeled first K iteration; epilogue reads them from LDS (no vmcnt(0) drain at epilogue start)
# speedup vs baseline: 1.0173x; 1.0056x over previous
; #define PG8_STAGE(bufoff, gbase, voff) do { _Pragma("unroll") for (int _i = 0; _i < 2; ++_i) \
;         __builtin_amdgcn_global_load_lds((const unsigned*)((const char*)(gbase) + (voff)[_i]), (LAS unsigned*)(lds + (bufoff) + ldsw + _i * 8192), 16, 0, 0); } while (0)
; #define PG8_LDA(dst, b, h) do { _Pragma("unroll") for (int m = 0; m < 4; ++m) _Pragma("unroll") for (int k = 0; k < 2; ++k) dst[m][k] = *(const LAS bf16x8*)(lds + PG8_SA(b, h) + aoff + m * 2048 + k * 1024); } while (0)
; #define PG8_LDB(dst, b, h) do { _Pragma("unroll") for (int n = 0; n < 2; ++n) _Pragma("unroll") for (int k = 0; k < 2; ++k) dst[n][k] = *(const LAS bf16x8*)(lds + PG8_SB(b, h) + boff + n * 2048 + k * 1024); } while (0)
; #define PG8_WAIT_V(n) asm volatile("s_waitcnt vmcnt(" #n ")" ::: "memory")
; #define PG8_WAIT_L(n) asm volatile("s_waitcnt lgkmcnt(" #n ")" ::: "memory")
; #define PG8_BAR __builtin_amdgcn_s_barrier()
; template <class Epi>
; DEVI void gemm_phase(LAS unsigned char* lds, const Gemm g, const Epi& E) {
;     ...
;             PG8_LDB(B0, 0, 0); PG8_SCHED; PG8_LDA(At, 0, 0); PG8_STAGE(PG8_SA(1, 1), a1 + hstepA, voffA);
;             PG8_WAIT_L(8); PG8_BAR; PG8_WAIT_L(0); PG8_MMA(0, 0, At, B0); PG8_BAR; PG8_SCHED;
;             PG8_LDB(B1, 0, 1); PG8_STAGE(PG8_SB(0, 0), b2, voffB);
;             PG8_BAR; PG8_WAIT_L(0); PG8_MMA(0, 1, At, B1); PG8_BAR;
;             PG8_LDA(At, 0, 1); PG8_STAGE(PG8_SA(0, 0), a2, voffA);
;             PG8_BAR; PG8_WAIT_L(0); PG8_MMA(1, 0, At, B0); PG8_BAR; PG8_SCHED;
;             PG8_STAGE(PG8_SB(0, 1), b2 + hstepB, voffB);
;             PG8_WAIT_V(6); PG8_BAR; PG8_MMA(1, 1, At, B1); PG8_BAR;
;             PG8_LDB(B0, 1, 0); PG8_SCHED; PG8_LDA(At, 1, 0); PG8_STAGE(PG8_SA(0, 1), a2 + hstepA, voffA);
;             PG8_WAIT_L(8); PG8_BAR; PG8_WAIT_L(0); PG8_MMA(0, 0, At, B0); PG8_BAR; PG8_SCHED;
;             PG8_LDB(B1, 1, 1); PG8_STAGE(PG8_SB(1, 0), b3, voffB);
;             PG8_BAR; PG8_WAIT_L(0); PG8_MMA(0, 1, At, B1); PG8_BAR;
;             PG8_LDA(At, 1, 1); PG8_STAGE(PG8_SA(1, 0), a3, voffA);
;             PG8_BAR; PG8_WAIT_L(0); PG8_MMA(1, 0, At, B0); PG8_BAR; PG8_SCHED;
;             PG8_STAGE(PG8_SB(1, 1), b3 + hstepB, voffB);
;             PG8_WAIT_V(6); PG8_BAR; PG8_MMA(1, 1, At, B1); PG8_BAR;
;     ...
;                 for (int i = 0; i < 8; ++i) q4[i] = *(const f32x4*)(E.ssq_in + (size_t)(row0 + (i >> 2) * HALF + (i & 3) * 16) * 4);
.LBB0_1671:
	s_ashr_i32 s7, s6, 31
	s_lshl_b64 s[0:1], s[6:7], 19
	v_cmp_lt_i64_e32 vcc, s[12:13], v[174:175]
	s_add_u32 s12, s24, s0
	s_addc_u32 s13, s25, s1
	s_and_b64 s[0:1], vcc, exec
	s_cselect_b32 s0, s13, s17
	s_cselect_b32 s1, s12, s16
	s_ashr_i32 s9, s8, 31
	s_lshl_b64 s[14:15], s[8:9], 19
	s_add_u32 s14, s68, s14
	s_addc_u32 s15, s69, s15
	s_and_b64 s[18:19], vcc, exec
	s_cselect_b32 s5, s15, s37
	s_cselect_b32 s7, s14, s36
	s_add_u32 s16, s16, 0x40080
	s_addc_u32 s17, s17, 0
	s_add_u32 s9, s36, 0x100
	s_addc_u32 s18, s37, 0
	s_mov_b32 s19, -2
	v_and_b32_e32 v248, 0xff, v154
	v_lshlrev_b32_e32 v248, 4, v248
	v_add_u32_e32 v249, 0x21000, v248
	v_lshl_add_u32 v248, s4, 12, v248
	global_load_dwordx4 v[244:247], v248, s[10:11]
	s_add_u32 s26, s16, 0xfffc0080
	s_addc_u32 s27, s17, -1
	s_add_i32 s38, 0, 0x10000
	v_add_u32_e32 v142, s38, v197
	ds_read_b128 v[130:133], v142
	ds_read_b128 v[134:137], v142 offset:1024
	ds_read_b128 v[138:141], v142 offset:2048
	ds_read_b128 v[142:145], v142 offset:3072
	s_cmp_eq_u32 s19, 12
	s_cselect_b32 s47, s0, s27
	s_cselect_b32 s46, s1, s26
	s_cselect_b32 s37, s5, s18
	s_cselect_b32 s36, s7, s9
	v_lshl_add_u64 v[162:163], s[16:17], 0, v[152:153]
	s_add_i32 m0, s79, 0xc000
	ds_read_b128 v[178:181], v201
	ds_read_b128 v[182:185], v201 offset:1024
	ds_read_b128 v[186:189], v201 offset:2048
	ds_read_b128 v[202:205], v201 offset:3072
	ds_read_b128 v[206:209], v201 offset:4096
	ds_read_b128 v[214:217], v201 offset:5120
	ds_read_b128 v[218:221], v201 offset:6144
	ds_read_b128 v[222:225], v201 offset:7168
	global_load_lds_dwordx4 v[162:163], off
	s_add_i32 m0, s79, 0xe000
	v_lshl_add_u64 v[162:163], s[16:17], 0, v[176:177]
	global_load_lds_dwordx4 v[162:163], off
	s_waitcnt lgkmcnt(8)
	s_barrier
	s_waitcnt lgkmcnt(0)
	v_mfma_f32_16x16x32_bf16 v[126:129], v[130:133], v[178:181], 0
	v_mfma_f32_16x16x32_bf16 v[122:125], v[138:141], v[178:181], 0
	v_mfma_f32_16x16x32_bf16 v[110:113], v[130:133], v[186:189], 0
	v_mfma_f32_16x16x32_bf16 v[106:109], v[138:141], v[186:189], 0
	v_mfma_f32_16x16x32_bf16 v[94:97], v[130:133], v[206:209], 0
	v_mfma_f32_16x16x32_bf16 v[90:93], v[138:141], v[206:209], 0
	v_mfma_f32_16x16x32_bf16 v[78:81], v[130:133], v[218:221], 0
	v_mfma_f32_16x16x32_bf16 v[74:77], v[138:141], v[218:221], 0
	v_mfma_f32_16x16x32_bf16 v[126:129], v[134:137], v[182:185], v[126:129]
	v_mfma_f32_16x16x32_bf16 v[122:125], v[142:145], v[182:185], v[122:125]
	v_mfma_f32_16x16x32_bf16 v[110:113], v[134:137], v[202:205], v[110:113]
	v_mfma_f32_16x16x32_bf16 v[106:109], v[142:145], v[202:205], v[106:109]
	v_mfma_f32_16x16x32_bf16 v[94:97], v[134:137], v[214:217], v[94:97]
	v_mfma_f32_16x16x32_bf16 v[90:93], v[142:145], v[214:217], v[90:93]
	v_mfma_f32_16x16x32_bf16 v[78:81], v[134:137], v[222:225], v[78:81]
	v_mfma_f32_16x16x32_bf16 v[74:77], v[142:145], v[222:225], v[74:77]
	s_barrier
	s_add_i32 s39, 0, 0x14000
	v_add_u32_e32 v162, s39, v197
	s_add_i32 s26, s38, s78
	ds_read_b128 v[226:229], v162
	ds_read_b128 v[230:233], v162 offset:1024
	ds_read_b128 v[234:237], v162 offset:2048
	ds_read_b128 v[238:241], v162 offset:3072
	v_lshl_add_u64 v[162:163], s[36:37], 0, v[8:9]
	s_mov_b32 m0, s26
	v_lshl_add_u64 v[164:165], s[36:37], 0, v[146:147]
	global_load_lds_dwordx4 v[162:163], off
	s_add_i32 m0, s26, 0x2000
	s_nop 0
	global_load_lds_dwordx4 v[164:165], off
	s_barrier
	s_waitcnt lgkmcnt(0)
	v_mfma_f32_16x16x32_bf16 v[118:121], v[226:229], v[178:181], 0
	v_mfma_f32_16x16x32_bf16 v[114:117], v[234:237], v[178:181], 0
	v_mfma_f32_16x16x32_bf16 v[102:105], v[226:229], v[186:189], 0
	v_mfma_f32_16x16x32_bf16 v[98:101], v[234:237], v[186:189], 0
	v_mfma_f32_16x16x32_bf16 v[86:89], v[226:229], v[206:209], 0
	v_mfma_f32_16x16x32_bf16 v[82:85], v[234:237], v[206:209], 0
	v_mfma_f32_16x16x32_bf16 v[70:73], v[226:229], v[218:221], 0
	v_mfma_f32_16x16x32_bf16 v[66:69], v[234:237], v[218:221], 0
	v_mfma_f32_16x16x32_bf16 v[118:121], v[230:233], v[182:185], v[118:121]
	v_mfma_f32_16x16x32_bf16 v[114:117], v[238:241], v[182:185], v[114:117]
	v_mfma_f32_16x16x32_bf16 v[102:105], v[230:233], v[202:205], v[102:105]
	v_mfma_f32_16x16x32_bf16 v[98:101], v[238:241], v[202:205], v[98:101]
	v_mfma_f32_16x16x32_bf16 v[86:89], v[230:233], v[214:217], v[86:89]
	v_mfma_f32_16x16x32_bf16 v[82:85], v[238:241], v[214:217], v[82:85]
	v_mfma_f32_16x16x32_bf16 v[70:73], v[230:233], v[222:225], v[70:73]
	v_mfma_f32_16x16x32_bf16 v[66:69], v[238:241], v[222:225], v[66:69]
	s_mov_b32 m0, s79
	v_lshl_add_u64 v[190:191], s[46:47], 0, v[150:151]
	s_barrier
	ds_read_b128 v[178:181], v201 offset:16384
	ds_read_b128 v[182:185], v201 offset:17408
	ds_read_b128 v[186:189], v201 offset:18432
	ds_read_b128 v[202:205], v201 offset:19456
	ds_read_b128 v[206:209], v201 offset:20480
	ds_read_b128 v[214:217], v201 offset:21504
	ds_read_b128 v[218:221], v201 offset:22528
	ds_read_b128 v[222:225], v201 offset:23552
	global_load_lds_dwordx4 v[190:191], off
	s_mov_b32 m0, s80
	v_lshl_add_u64 v[194:195], s[46:47], 0, v[148:149]
	global_load_lds_dwordx4 v[194:195], off
	s_barrier
	s_waitcnt lgkmcnt(0)
	v_mfma_f32_16x16x32_bf16 v[50:53], v[130:133], v[178:181], 0
	v_mfma_f32_16x16x32_bf16 v[54:57], v[138:141], v[178:181], 0
	v_mfma_f32_16x16x32_bf16 v[34:37], v[130:133], v[186:189], 0
	v_mfma_f32_16x16x32_bf16 v[38:41], v[138:141], v[186:189], 0
	v_mfma_f32_16x16x32_bf16 v[18:21], v[130:133], v[206:209], 0
	v_mfma_f32_16x16x32_bf16 v[22:25], v[138:141], v[206:209], 0
	v_mfma_f32_16x16x32_bf16 v[0:3], v[130:133], v[218:221], 0
	v_mfma_f32_16x16x32_bf16 v[4:7], v[138:141], v[218:221], 0
	v_mfma_f32_16x16x32_bf16 v[50:53], v[134:137], v[182:185], v[50:53]
	v_mfma_f32_16x16x32_bf16 v[54:57], v[142:145], v[182:185], v[54:57]
	v_mfma_f32_16x16x32_bf16 v[34:37], v[134:137], v[202:205], v[34:37]
	v_mfma_f32_16x16x32_bf16 v[38:41], v[142:145], v[202:205], v[38:41]
	v_mfma_f32_16x16x32_bf16 v[18:21], v[134:137], v[214:217], v[18:21]
	v_mfma_f32_16x16x32_bf16 v[22:25], v[142:145], v[214:217], v[22:25]
	v_mfma_f32_16x16x32_bf16 v[0:3], v[134:137], v[222:225], v[0:3]
	v_mfma_f32_16x16x32_bf16 v[4:7], v[142:145], v[222:225], v[4:7]
	s_barrier
; #define PG8_STAGE(bufoff, gbase, voff) do { _Pragma("unroll") for (int _i = 0; _i < 2; ++_i) \
;         __builtin_amdgcn_global_load_lds((const unsigned*)((const char*)(gbase) + (voff)[_i]), (LAS unsigned*)(lds + (bufoff) + ldsw + _i * 8192), 16, 0, 0); } while (0)
; #define PG8_LDA(dst, b, h) do { _Pragma("unroll") for (int m = 0; m < 4; ++m) _Pragma("unroll") for (int k = 0; k < 2; ++k) dst[m][k] = *(const LAS bf16x8*)(lds + PG8_SA(b, h) + aoff + m * 2048 + k * 1024); } while (0)
; #define PG8_LDB(dst, b, h) do { _Pragma("unroll") for (int n = 0; n < 2; ++n) _Pragma("unroll") for (int k = 0; k < 2; ++k) dst[n][k] = *(const LAS bf16x8*)(lds + PG8_SB(b, h) + boff + n * 2048 + k * 1024); } while (0)
; #define PG8_MMA(ai, bj, At, Bt) do { __builtin_amdgcn_s_setprio(1); _Pragma("unroll") for (int m = 0; m < 4; ++m) _Pragma("unroll") for (int n = 0; n < 2; ++n) _Pragma("unroll") for (int k = 0; k < 2; ++k) \
;         acc[ai][bj][m][n] = __builtin_amdgcn_mfma_f32_16x16x32_bf16(Bt[n][k], At[m][k], acc[ai][bj][m][n], 0, 0, 0); __builtin_amdgcn_s_setprio(0); } while (0)
; #define PG8_WAIT_V(n) asm volatile("s_waitcnt vmcnt(" #n ")" ::: "memory")
; #define PG8_WAIT_L(n) asm volatile("s_waitcnt lgkmcnt(" #n ")" ::: "memory")
; #define PG8_BAR __builtin_amdgcn_s_barrier()
; #define PG8_SCHED __builtin_amdgcn_sched_barrier(0)
; template <class Epi>
; DEVI void gemm_phase(LAS unsigned char* lds, const Gemm g, const Epi& E) {
;     ...
;             PG8_BAR; PG8_WAIT_L(0); PG8_MMA(1, 0, At, B0); PG8_BAR; PG8_SCHED;
;             PG8_STAGE(PG8_SB(0, 1), b2 + hstepB, voffB);
;             PG8_WAIT_V(6); PG8_BAR; PG8_MMA(1, 1, At, B1); PG8_BAR;
;             PG8_LDB(B0, 1, 0); PG8_SCHED; PG8_LDA(At, 1, 0); PG8_STAGE(PG8_SA(0, 1), a2 + hstepA, voffA);
;             PG8_WAIT_L(8); PG8_BAR; PG8_WAIT_L(0); PG8_MMA(0, 0, At, B0); PG8_BAR; PG8_SCHED;
;             PG8_LDB(B1, 1, 1); PG8_STAGE(PG8_SB(1, 0), b3, voffB);
;             PG8_BAR; PG8_WAIT_L(0); PG8_MMA(0, 1, At, B1); PG8_BAR;
;             PG8_LDA(At, 1, 1); PG8_STAGE(PG8_SA(1, 0), a3, voffA);
;             PG8_BAR; PG8_WAIT_L(0); PG8_MMA(1, 0, At, B0); PG8_BAR; PG8_SCHED;
;             PG8_STAGE(PG8_SB(1, 1), b3 + hstepB, voffB);
;             PG8_WAIT_V(6); PG8_BAR; PG8_MMA(1, 1, At, B1); PG8_BAR;
	s_add_u32 s26, s36, 0x40000
	s_addc_u32 s27, s37, 0
	s_add_i32 s38, s39, s78
	s_mov_b32 m0, s38
	v_lshl_add_u64 v[130:131], s[26:27], 0, v[8:9]
	global_load_lds_dwordx4 v[130:131], off
	s_add_i32 m0, s38, 0x2000
	v_lshl_add_u64 v[130:131], s[26:27], 0, v[146:147]
	global_load_lds_dwordx4 v[130:131], off
	s_waitcnt vmcnt(6)
	ds_write_b128 v249, v[244:247]
	s_barrier
	v_mfma_f32_16x16x32_bf16 v[58:61], v[226:229], v[178:181], 0
	v_mfma_f32_16x16x32_bf16 v[62:65], v[234:237], v[178:181], 0
	v_mfma_f32_16x16x32_bf16 v[42:45], v[226:229], v[186:189], 0
	v_mfma_f32_16x16x32_bf16 v[46:49], v[234:237], v[186:189], 0
	v_mfma_f32_16x16x32_bf16 v[26:29], v[226:229], v[206:209], 0
	v_mfma_f32_16x16x32_bf16 v[30:33], v[234:237], v[206:209], 0
	v_mfma_f32_16x16x32_bf16 v[10:13], v[226:229], v[218:221], 0
	v_mfma_f32_16x16x32_bf16 v[14:17], v[234:237], v[218:221], 0
	v_mfma_f32_16x16x32_bf16 v[58:61], v[230:233], v[182:185], v[58:61]
	v_mfma_f32_16x16x32_bf16 v[62:65], v[238:241], v[182:185], v[62:65]
	v_mfma_f32_16x16x32_bf16 v[42:45], v[230:233], v[202:205], v[42:45]
	v_mfma_f32_16x16x32_bf16 v[46:49], v[238:241], v[202:205], v[46:49]
	v_mfma_f32_16x16x32_bf16 v[26:29], v[230:233], v[214:217], v[26:29]
	v_mfma_f32_16x16x32_bf16 v[30:33], v[238:241], v[214:217], v[30:33]
	v_mfma_f32_16x16x32_bf16 v[10:13], v[230:233], v[222:225], v[10:13]
	v_mfma_f32_16x16x32_bf16 v[14:17], v[238:241], v[222:225], v[14:17]
	s_add_i32 s38, 0, 0x18000
	v_add_u32_e32 v142, s38, v197
	s_barrier
	ds_read_b128 v[130:133], v142
	ds_read_b128 v[134:137], v142 offset:1024
	ds_read_b128 v[138:141], v142 offset:2048
	ds_read_b128 v[142:145], v142 offset:3072
	s_add_u32 s26, s46, 0x40000
	s_addc_u32 s27, s47, 0
	s_mov_b32 m0, s81
	v_lshl_add_u64 v[226:227], s[26:27], 0, v[150:151]
	ds_read_b128 v[178:181], v201 offset:32768
	ds_read_b128 v[182:185], v201 offset:33792
	ds_read_b128 v[186:189], v201 offset:34816
	ds_read_b128 v[202:205], v201 offset:35840
	ds_read_b128 v[206:209], v201 offset:36864
	ds_read_b128 v[214:217], v201 offset:37888
	ds_read_b128 v[218:221], v201 offset:38912
	ds_read_b128 v[222:225], v201 offset:39936
	global_load_lds_dwordx4 v[226:227], off
	s_mov_b32 m0, s82
	v_lshl_add_u64 v[226:227], s[26:27], 0, v[148:149]
	global_load_lds_dwordx4 v[226:227], off
	s_waitcnt lgkmcnt(8)
	s_barrier
	s_waitcnt lgkmcnt(0)
	v_mfma_f32_16x16x32_bf16 v[126:129], v[130:133], v[178:181], v[126:129]
	v_mfma_f32_16x16x32_bf16 v[122:125], v[138:141], v[178:181], v[122:125]
	v_mfma_f32_16x16x32_bf16 v[110:113], v[130:133], v[186:189], v[110:113]
	v_mfma_f32_16x16x32_bf16 v[106:109], v[138:141], v[186:189], v[106:109]
	v_mfma_f32_16x16x32_bf16 v[94:97], v[130:133], v[206:209], v[94:97]
	v_mfma_f32_16x16x32_bf16 v[90:93], v[138:141], v[206:209], v[90:93]
	v_mfma_f32_16x16x32_bf16 v[78:81], v[130:133], v[218:221], v[78:81]
	v_mfma_f32_16x16x32_bf16 v[74:77], v[138:141], v[218:221], v[74:77]
	v_mfma_f32_16x16x32_bf16 v[126:129], v[134:137], v[182:185], v[126:129]
	v_mfma_f32_16x16x32_bf16 v[122:125], v[142:145], v[182:185], v[122:125]
	v_mfma_f32_16x16x32_bf16 v[110:113], v[134:137], v[202:205], v[110:113]
	v_mfma_f32_16x16x32_bf16 v[106:109], v[142:145], v[202:205], v[106:109]
	v_mfma_f32_16x16x32_bf16 v[94:97], v[134:137], v[214:217], v[94:97]
	v_mfma_f32_16x16x32_bf16 v[90:93], v[142:145], v[214:217], v[90:93]
	v_mfma_f32_16x16x32_bf16 v[78:81], v[134:137], v[222:225], v[78:81]
	v_mfma_f32_16x16x32_bf16 v[74:77], v[142:145], v[222:225], v[74:77]
	s_barrier
	s_add_i32 s39, 0, 0x1c000
	s_add_i32 s26, s38, s78
	v_add_u32_e32 v192, s39, v197
	v_lshl_add_u64 v[162:163], v[162:163], 0, s[70:71]
	s_mov_b32 m0, s26
	ds_read_b128 v[226:229], v192
	ds_read_b128 v[230:233], v192 offset:1024
	ds_read_b128 v[234:237], v192 offset:2048
	ds_read_b128 v[238:241], v192 offset:3072
	global_load_lds_dwordx4 v[162:163], off
	s_add_i32 m0, s26, 0x2000
	v_lshl_add_u64 v[162:163], v[164:165], 0, s[70:71]
	global_load_lds_dwordx4 v[162:163], off
	s_barrier
	s_waitcnt lgkmcnt(0)
	v_mfma_f32_16x16x32_bf16 v[118:121], v[226:229], v[178:181], v[118:121]
	v_mfma_f32_16x16x32_bf16 v[114:117], v[234:237], v[178:181], v[114:117]
	v_mfma_f32_16x16x32_bf16 v[102:105], v[226:229], v[186:189], v[102:105]
	v_mfma_f32_16x16x32_bf16 v[98:101], v[234:237], v[186:189], v[98:101]
	v_mfma_f32_16x16x32_bf16 v[86:89], v[226:229], v[206:209], v[86:89]
	v_mfma_f32_16x16x32_bf16 v[82:85], v[234:237], v[206:209], v[82:85]
	v_mfma_f32_16x16x32_bf16 v[70:73], v[226:229], v[218:221], v[70:73]
	v_mfma_f32_16x16x32_bf16 v[66:69], v[234:237], v[218:221], v[66:69]
	v_mfma_f32_16x16x32_bf16 v[118:121], v[230:233], v[182:185], v[118:121]
	v_mfma_f32_16x16x32_bf16 v[114:117], v[238:241], v[182:185], v[114:117]
	v_mfma_f32_16x16x32_bf16 v[102:105], v[230:233], v[202:205], v[102:105]
	v_mfma_f32_16x16x32_bf16 v[98:101], v[238:241], v[202:205], v[98:101]
	v_mfma_f32_16x16x32_bf16 v[86:89], v[230:233], v[214:217], v[86:89]
	v_mfma_f32_16x16x32_bf16 v[82:85], v[238:241], v[214:217], v[82:85]
	v_mfma_f32_16x16x32_bf16 v[70:73], v[230:233], v[222:225], v[70:73]
	v_mfma_f32_16x16x32_bf16 v[66:69], v[238:241], v[222:225], v[66:69]
	s_mov_b32 m0, s83
	v_lshl_add_u64 v[162:163], v[190:191], 0, s[70:71]
	s_barrier
	ds_read_b128 v[178:181], v201 offset:49152
	ds_read_b128 v[182:185], v201 offset:50176
	ds_read_b128 v[186:189], v201 offset:51200
	ds_read_b128 v[202:205], v201 offset:52224
	ds_read_b128 v[206:209], v201 offset:53248
	ds_read_b128 v[214:217], v201 offset:54272
	ds_read_b128 v[218:221], v201 offset:55296
	ds_read_b128 v[222:225], v201 offset:56320
	global_load_lds_dwordx4 v[162:163], off
	s_mov_b32 m0, s84
	v_lshl_add_u64 v[162:163], v[194:195], 0, s[70:71]
	global_load_lds_dwordx4 v[162:163], off
	s_barrier
; #define PG8_STAGE(bufoff, gbase, voff) do { _Pragma("unroll") for (int _i = 0; _i < 2; ++_i) \
;         __builtin_amdgcn_global_load_lds((const unsigned*)((const char*)(gbase) + (voff)[_i]), (LAS unsigned*)(lds + (bufoff) + ldsw + _i * 8192), 16, 0, 0); } while (0)
; #define PG8_LDA(dst, b, h) do { _Pragma("unroll") for (int m = 0; m < 4; ++m) _Pragma("unroll") for (int k = 0; k < 2; ++k) dst[m][k] = *(const LAS bf16x8*)(lds + PG8_SA(b, h) + aoff + m * 2048 + k * 1024); } while (0)
; #define PG8_LDB(dst, b, h) do { _Pragma("unroll") for (int n = 0; n < 2; ++n) _Pragma("unroll") for (int k = 0; k < 2; ++k) dst[n][k] = *(const LAS bf16x8*)(lds + PG8_SB(b, h) + boff + n * 2048 + k * 1024); } while (0)
; #define PG8_WAIT_V(n) asm volatile("s_waitcnt vmcnt(" #n ")" ::: "memory")
; #define PG8_WAIT_L(n) asm volatile("s_waitcnt lgkmcnt(" #n ")" ::: "memory")
; #define PG8_BAR __builtin_amdgcn_s_barrier()
; #define PG8_SCHED __builtin_amdgcn_sched_barrier(0)
; template <class Epi>
; DEVI void gemm_phase(LAS unsigned char* lds, const Gemm g, const Epi& E) {
;     ...
;             PG8_LDB(B0, 0, 0); PG8_SCHED; PG8_LDA(At, 0, 0); PG8_STAGE(PG8_SA(1, 1), a1 + hstepA, voffA);
;             PG8_WAIT_L(8); PG8_BAR; PG8_WAIT_L(0); PG8_MMA(0, 0, At, B0); PG8_BAR; PG8_SCHED;
;             PG8_LDB(B1, 0, 1); PG8_STAGE(PG8_SB(0, 0), b2, voffB);
;             PG8_BAR; PG8_WAIT_L(0); PG8_MMA(0, 1, At, B1); PG8_BAR;
;             PG8_LDA(At, 0, 1); PG8_STAGE(PG8_SA(0, 0), a2, voffA);
;             PG8_BAR; PG8_WAIT_L(0); PG8_MMA(1, 0, At, B0); PG8_BAR; PG8_SCHED;
;             PG8_STAGE(PG8_SB(0, 1), b2 + hstepB, voffB);
;             PG8_WAIT_V(6); PG8_BAR; PG8_MMA(1, 1, At, B1); PG8_BAR;
;             PG8_LDB(B0, 1, 0); PG8_SCHED; PG8_LDA(At, 1, 0); PG8_STAGE(PG8_SA(0, 1), a2 + hstepA, voffA);
;             PG8_WAIT_L(8); PG8_BAR; PG8_WAIT_L(0); PG8_MMA(0, 0, At, B0); PG8_BAR; PG8_SCHED;
;             PG8_LDB(B1, 1, 1); PG8_STAGE(PG8_SB(1, 0), b3, voffB);
;             PG8_BAR; PG8_WAIT_L(0); PG8_MMA(0, 1, At, B1); PG8_BAR;
;             PG8_LDA(At, 1, 1); PG8_STAGE(PG8_SA(1, 0), a3, voffA);
;             PG8_BAR; PG8_WAIT_L(0); PG8_MMA(1, 0, At, B0); PG8_BAR; PG8_SCHED;
;             PG8_STAGE(PG8_SB(1, 1), b3 + hstepB, voffB);
;             PG8_WAIT_V(6); PG8_BAR; PG8_MMA(1, 1, At, B1); PG8_BAR;
	s_waitcnt lgkmcnt(0)
	v_mfma_f32_16x16x32_bf16 v[50:53], v[130:133], v[178:181], v[50:53]
	v_mfma_f32_16x16x32_bf16 v[54:57], v[138:141], v[178:181], v[54:57]
	v_mfma_f32_16x16x32_bf16 v[34:37], v[130:133], v[186:189], v[34:37]
	v_mfma_f32_16x16x32_bf16 v[38:41], v[138:141], v[186:189], v[38:41]
	v_mfma_f32_16x16x32_bf16 v[18:21], v[130:133], v[206:209], v[18:21]
	v_mfma_f32_16x16x32_bf16 v[22:25], v[138:141], v[206:209], v[22:25]
	v_mfma_f32_16x16x32_bf16 v[0:3], v[130:133], v[218:221], v[0:3]
	v_mfma_f32_16x16x32_bf16 v[4:7], v[138:141], v[218:221], v[4:7]
	v_mfma_f32_16x16x32_bf16 v[50:53], v[134:137], v[182:185], v[50:53]
	v_mfma_f32_16x16x32_bf16 v[54:57], v[142:145], v[182:185], v[54:57]
	v_mfma_f32_16x16x32_bf16 v[34:37], v[134:137], v[202:205], v[34:37]
	v_mfma_f32_16x16x32_bf16 v[38:41], v[142:145], v[202:205], v[38:41]
	v_mfma_f32_16x16x32_bf16 v[18:21], v[134:137], v[214:217], v[18:21]
	v_mfma_f32_16x16x32_bf16 v[22:25], v[142:145], v[214:217], v[22:25]
	v_mfma_f32_16x16x32_bf16 v[0:3], v[134:137], v[222:225], v[0:3]
	v_mfma_f32_16x16x32_bf16 v[4:7], v[142:145], v[222:225], v[4:7]
	s_barrier
	s_add_u32 s26, s36, 0x40080
	s_addc_u32 s27, s37, 0
	s_add_i32 s36, s39, s78
	s_mov_b32 m0, s36
	v_lshl_add_u64 v[130:131], s[26:27], 0, v[8:9]
	global_load_lds_dwordx4 v[130:131], off
	s_add_i32 m0, s36, 0x2000
	v_lshl_add_u64 v[130:131], s[26:27], 0, v[146:147]
	global_load_lds_dwordx4 v[130:131], off
	s_waitcnt vmcnt(6)
	s_barrier
	v_mfma_f32_16x16x32_bf16 v[58:61], v[226:229], v[178:181], v[58:61]
	v_mfma_f32_16x16x32_bf16 v[62:65], v[234:237], v[178:181], v[62:65]
	v_mfma_f32_16x16x32_bf16 v[42:45], v[226:229], v[186:189], v[42:45]
	v_mfma_f32_16x16x32_bf16 v[46:49], v[234:237], v[186:189], v[46:49]
	v_mfma_f32_16x16x32_bf16 v[26:29], v[226:229], v[206:209], v[26:29]
	v_mfma_f32_16x16x32_bf16 v[30:33], v[234:237], v[206:209], v[30:33]
	v_mfma_f32_16x16x32_bf16 v[10:13], v[226:229], v[218:221], v[10:13]
	v_mfma_f32_16x16x32_bf16 v[14:17], v[234:237], v[218:221], v[14:17]
	v_mfma_f32_16x16x32_bf16 v[58:61], v[230:233], v[182:185], v[58:61]
	v_mfma_f32_16x16x32_bf16 v[62:65], v[238:241], v[182:185], v[62:65]
	v_mfma_f32_16x16x32_bf16 v[42:45], v[230:233], v[202:205], v[42:45]
	v_mfma_f32_16x16x32_bf16 v[46:49], v[238:241], v[202:205], v[46:49]
	v_mfma_f32_16x16x32_bf16 v[26:29], v[230:233], v[214:217], v[26:29]
	v_mfma_f32_16x16x32_bf16 v[30:33], v[238:241], v[214:217], v[30:33]
	v_mfma_f32_16x16x32_bf16 v[10:13], v[230:233], v[222:225], v[10:13]
	v_mfma_f32_16x16x32_bf16 v[14:17], v[238:241], v[222:225], v[14:17]
	s_add_i32 s19, s19, 2
	s_add_u32 s16, s16, 0x100
	s_addc_u32 s17, s17, 0
	s_add_u32 s9, s9, 0x100
	s_addc_u32 s18, s18, 0
	s_cmp_gt_u32 s19, 13
	s_barrier
.LBB0_1672:
	s_add_u32 s26, s16, 0xfffc0080
	s_addc_u32 s27, s17, -1
	s_add_i32 s38, 0, 0x10000
	v_add_u32_e32 v142, s38, v197
	ds_read_b128 v[130:133], v142
	ds_read_b128 v[134:137], v142 offset:1024
	ds_read_b128 v[138:141], v142 offset:2048
	ds_read_b128 v[142:145], v142 offset:3072
	s_cmp_eq_u32 s19, 12
	s_cselect_b32 s47, s0, s27
	s_cselect_b32 s46, s1, s26
	s_cselect_b32 s37, s5, s18
	s_cselect_b32 s36, s7, s9
	v_lshl_add_u64 v[162:163], s[16:17], 0, v[152:153]
	s_add_i32 m0, s79, 0xc000
	ds_read_b128 v[178:181], v201
	ds_read_b128 v[182:185], v201 offset:1024
	ds_read_b128 v[186:189], v201 offset:2048
	ds_read_b128 v[202:205], v201 offset:3072
	ds_read_b128 v[206:209], v201 offset:4096
	ds_read_b128 v[214:217], v201 offset:5120
	ds_read_b128 v[218:221], v201 offset:6144
	ds_read_b128 v[222:225], v201 offset:7168
	global_load_lds_dwordx4 v[162:163], off
	s_add_i32 m0, s79, 0xe000
	v_lshl_add_u64 v[162:163], s[16:17], 0, v[176:177]
	global_load_lds_dwordx4 v[162:163], off
	s_waitcnt lgkmcnt(8)
	s_barrier
	s_waitcnt lgkmcnt(0)
	v_mfma_f32_16x16x32_bf16 v[126:129], v[130:133], v[178:181], v[126:129]
	v_mfma_f32_16x16x32_bf16 v[122:125], v[138:141], v[178:181], v[122:125]
	v_mfma_f32_16x16x32_bf16 v[110:113], v[130:133], v[186:189], v[110:113]
	v_mfma_f32_16x16x32_bf16 v[106:109], v[138:141], v[186:189], v[106:109]
	v_mfma_f32_16x16x32_bf16 v[94:97], v[130:133], v[206:209], v[94:97]
	v_mfma_f32_16x16x32_bf16 v[90:93], v[138:141], v[206:209], v[90:93]
	v_mfma_f32_16x16x32_bf16 v[78:81], v[130:133], v[218:221], v[78:81]
	v_mfma_f32_16x16x32_bf16 v[74:77], v[138:141], v[218:221], v[74:77]
	v_mfma_f32_16x16x32_bf16 v[126:129], v[134:137], v[182:185], v[126:129]
	v_mfma_f32_16x16x32_bf16 v[122:125], v[142:145], v[182:185], v[122:125]
	v_mfma_f32_16x16x32_bf16 v[110:113], v[134:137], v[202:205], v[110:113]
	v_mfma_f32_16x16x32_bf16 v[106:109], v[142:145], v[202:205], v[106:109]
	v_mfma_f32_16x16x32_bf16 v[94:97], v[134:137], v[214:217], v[94:97]
	v_mfma_f32_16x16x32_bf16 v[90:93], v[142:145], v[214:217], v[90:93]
	v_mfma_f32_16x16x32_bf16 v[78:81], v[134:137], v[222:225], v[78:81]
	v_mfma_f32_16x16x32_bf16 v[74:77], v[142:145], v[222:225], v[74:77]
	s_barrier
	s_add_i32 s39, 0, 0x14000
	v_add_u32_e32 v162, s39, v197
	s_add_i32 s26, s38, s78
	ds_read_b128 v[226:229], v162
	ds_read_b128 v[230:233], v162 offset:1024
	ds_read_b128 v[234:237], v162 offset:2048
	ds_read_b128 v[238:241], v162 offset:3072
	v_lshl_add_u64 v[162:163], s[36:37], 0, v[8:9]
	s_mov_b32 m0, s26
	v_lshl_add_u64 v[164:165], s[36:37], 0, v[146:147]
	global_load_lds_dwordx4 v[162:163], off
	s_add_i32 m0, s26, 0x2000
	s_nop 0
	global_load_lds_dwordx4 v[164:165], off
	s_barrier
; #define PG8_STAGE(bufoff, gbase, voff) do { _Pragma("unroll") for (int _i = 0; _i < 2; ++_i) \
;         __builtin_amdgcn_global_load_lds((const unsigned*)((const char*)(gbase) + (voff)[_i]), (LAS unsigned*)(lds + (bufoff) + ldsw + _i * 8192), 16, 0, 0); } while (0)
; #define PG8_LDA(dst, b, h) do { _Pragma("unroll") for (int m = 0; m < 4; ++m) _Pragma("unroll") for (int k = 0; k < 2; ++k) dst[m][k] = *(const LAS bf16x8*)(lds + PG8_SA(b, h) + aoff + m * 2048 + k * 1024); } while (0)
; #define PG8_LDB(dst, b, h) do { _Pragma("unroll") for (int n = 0; n < 2; ++n) _Pragma("unroll") for (int k = 0; k < 2; ++k) dst[n][k] = *(const LAS bf16x8*)(lds + PG8_SB(b, h) + boff + n * 2048 + k * 1024); } while (0)
; #define PG8_MMA(ai, bj, At, Bt) do { __builtin_amdgcn_s_setprio(1); _Pragma("unroll") for (int m = 0; m < 4; ++m) _Pragma("unroll") for (int n = 0; n < 2; ++n) _Pragma("unroll") for (int k = 0; k < 2; ++k) \
;         acc[ai][bj][m][n] = __builtin_amdgcn_mfma_f32_16x16x32_bf16(Bt[n][k], At[m][k], acc[ai][bj][m][n], 0, 0, 0); __builtin_amdgcn_s_setprio(0); } while (0)
; #define PG8_WAIT_V(n) asm volatile("s_waitcnt vmcnt(" #n ")" ::: "memory")
; #define PG8_WAIT_L(n) asm volatile("s_waitcnt lgkmcnt(" #n ")" ::: "memory")
; #define PG8_BAR __builtin_amdgcn_s_barrier()
; #define PG8_SCHED __builtin_amdgcn_sched_barrier(0)
; template <class Epi>
; DEVI void gemm_phase(LAS unsigned char* lds, const Gemm g, const Epi& E) {
;     ...
;             PG8_BAR; PG8_WAIT_L(0); PG8_MMA(0, 1, At, B1); PG8_BAR;
;             PG8_LDA(At, 0, 1); PG8_STAGE(PG8_SA(0, 0), a2, voffA);
;             PG8_BAR; PG8_WAIT_L(0); PG8_MMA(1, 0, At, B0); PG8_BAR; PG8_SCHED;
;             PG8_STAGE(PG8_SB(0, 1), b2 + hstepB, voffB);
;             PG8_WAIT_V(6); PG8_BAR; PG8_MMA(1, 1, At, B1); PG8_BAR;
;             PG8_LDB(B0, 1, 0); PG8_SCHED; PG8_LDA(At, 1, 0); PG8_STAGE(PG8_SA(0, 1), a2 + hstepA, voffA);
;             PG8_WAIT_L(8); PG8_BAR; PG8_WAIT_L(0); PG8_MMA(0, 0, At, B0); PG8_BAR; PG8_SCHED;
;             PG8_LDB(B1, 1, 1); PG8_STAGE(PG8_SB(1, 0), b3, voffB);
;             PG8_BAR; PG8_WAIT_L(0); PG8_MMA(0, 1, At, B1); PG8_BAR;
;             PG8_LDA(At, 1, 1); PG8_STAGE(PG8_SA(1, 0), a3, voffA);
;             PG8_BAR; PG8_WAIT_L(0); PG8_MMA(1, 0, At, B0); PG8_BAR; PG8_SCHED;
	s_waitcnt lgkmcnt(0)
	v_mfma_f32_16x16x32_bf16 v[118:121], v[226:229], v[178:181], v[118:121]
	v_mfma_f32_16x16x32_bf16 v[114:117], v[234:237], v[178:181], v[114:117]
	v_mfma_f32_16x16x32_bf16 v[102:105], v[226:229], v[186:189], v[102:105]
	v_mfma_f32_16x16x32_bf16 v[98:101], v[234:237], v[186:189], v[98:101]
	v_mfma_f32_16x16x32_bf16 v[86:89], v[226:229], v[206:209], v[86:89]
	v_mfma_f32_16x16x32_bf16 v[82:85], v[234:237], v[206:209], v[82:85]
	v_mfma_f32_16x16x32_bf16 v[70:73], v[226:229], v[218:221], v[70:73]
	v_mfma_f32_16x16x32_bf16 v[66:69], v[234:237], v[218:221], v[66:69]
	v_mfma_f32_16x16x32_bf16 v[118:121], v[230:233], v[182:185], v[118:121]
	v_mfma_f32_16x16x32_bf16 v[114:117], v[238:241], v[182:185], v[114:117]
	v_mfma_f32_16x16x32_bf16 v[102:105], v[230:233], v[202:205], v[102:105]
	v_mfma_f32_16x16x32_bf16 v[98:101], v[238:241], v[202:205], v[98:101]
	v_mfma_f32_16x16x32_bf16 v[86:89], v[230:233], v[214:217], v[86:89]
	v_mfma_f32_16x16x32_bf16 v[82:85], v[238:241], v[214:217], v[82:85]
	v_mfma_f32_16x16x32_bf16 v[70:73], v[230:233], v[222:225], v[70:73]
	v_mfma_f32_16x16x32_bf16 v[66:69], v[238:241], v[222:225], v[66:69]
	s_mov_b32 m0, s79
	v_lshl_add_u64 v[190:191], s[46:47], 0, v[150:151]
	s_barrier
	ds_read_b128 v[178:181], v201 offset:16384
	ds_read_b128 v[182:185], v201 offset:17408
	ds_read_b128 v[186:189], v201 offset:18432
	ds_read_b128 v[202:205], v201 offset:19456
	ds_read_b128 v[206:209], v201 offset:20480
	ds_read_b128 v[214:217], v201 offset:21504
	ds_read_b128 v[218:221], v201 offset:22528
	ds_read_b128 v[222:225], v201 offset:23552
	global_load_lds_dwordx4 v[190:191], off
	s_mov_b32 m0, s80
	v_lshl_add_u64 v[194:195], s[46:47], 0, v[148:149]
	global_load_lds_dwordx4 v[194:195], off
	s_barrier
	s_waitcnt lgkmcnt(0)
	v_mfma_f32_16x16x32_bf16 v[50:53], v[130:133], v[178:181], v[50:53]
	v_mfma_f32_16x16x32_bf16 v[54:57], v[138:141], v[178:181], v[54:57]
	v_mfma_f32_16x16x32_bf16 v[34:37], v[130:133], v[186:189], v[34:37]
	v_mfma_f32_16x16x32_bf16 v[38:41], v[138:141], v[186:189], v[38:41]
	v_mfma_f32_16x16x32_bf16 v[18:21], v[130:133], v[206:209], v[18:21]
	v_mfma_f32_16x16x32_bf16 v[22:25], v[138:141], v[206:209], v[22:25]
	v_mfma_f32_16x16x32_bf16 v[0:3], v[130:133], v[218:221], v[0:3]
	v_mfma_f32_16x16x32_bf16 v[4:7], v[138:141], v[218:221], v[4:7]
	v_mfma_f32_16x16x32_bf16 v[50:53], v[134:137], v[182:185], v[50:53]
	v_mfma_f32_16x16x32_bf16 v[54:57], v[142:145], v[182:185], v[54:57]
	v_mfma_f32_16x16x32_bf16 v[34:37], v[134:137], v[202:205], v[34:37]
	v_mfma_f32_16x16x32_bf16 v[38:41], v[142:145], v[202:205], v[38:41]
	v_mfma_f32_16x16x32_bf16 v[18:21], v[134:137], v[214:217], v[18:21]
	v_mfma_f32_16x16x32_bf16 v[22:25], v[142:145], v[214:217], v[22:25]
	v_mfma_f32_16x16x32_bf16 v[0:3], v[134:137], v[222:225], v[0:3]
	v_mfma_f32_16x16x32_bf16 v[4:7], v[142:145], v[222:225], v[4:7]
	s_barrier
	s_add_u32 s26, s36, 0x40000
	s_addc_u32 s27, s37, 0
	s_add_i32 s38, s39, s78
	s_mov_b32 m0, s38
	v_lshl_add_u64 v[130:131], s[26:27], 0, v[8:9]
	global_load_lds_dwordx4 v[130:131], off
	s_add_i32 m0, s38, 0x2000
	v_lshl_add_u64 v[130:131], s[26:27], 0, v[146:147]
	global_load_lds_dwordx4 v[130:131], off
	s_waitcnt vmcnt(6)
	s_barrier
	v_mfma_f32_16x16x32_bf16 v[58:61], v[226:229], v[178:181], v[58:61]
	v_mfma_f32_16x16x32_bf16 v[62:65], v[234:237], v[178:181], v[62:65]
	v_mfma_f32_16x16x32_bf16 v[42:45], v[226:229], v[186:189], v[42:45]
	v_mfma_f32_16x16x32_bf16 v[46:49], v[234:237], v[186:189], v[46:49]
	v_mfma_f32_16x16x32_bf16 v[26:29], v[226:229], v[206:209], v[26:29]
	v_mfma_f32_16x16x32_bf16 v[30:33], v[234:237], v[206:209], v[30:33]
	v_mfma_f32_16x16x32_bf16 v[10:13], v[226:229], v[218:221], v[10:13]
	v_mfma_f32_16x16x32_bf16 v[14:17], v[234:237], v[218:221], v[14:17]
	v_mfma_f32_16x16x32_bf16 v[58:61], v[230:233], v[182:185], v[58:61]
	v_mfma_f32_16x16x32_bf16 v[62:65], v[238:241], v[182:185], v[62:65]
	v_mfma_f32_16x16x32_bf16 v[42:45], v[230:233], v[202:205], v[42:45]
	v_mfma_f32_16x16x32_bf16 v[46:49], v[238:241], v[202:205], v[46:49]
	v_mfma_f32_16x16x32_bf16 v[26:29], v[230:233], v[214:217], v[26:29]
	v_mfma_f32_16x16x32_bf16 v[30:33], v[238:241], v[214:217], v[30:33]
	v_mfma_f32_16x16x32_bf16 v[10:13], v[230:233], v[222:225], v[10:13]
	v_mfma_f32_16x16x32_bf16 v[14:17], v[238:241], v[222:225], v[14:17]
	s_add_i32 s38, 0, 0x18000
	v_add_u32_e32 v142, s38, v197
	s_barrier
	ds_read_b128 v[130:133], v142
	ds_read_b128 v[134:137], v142 offset:1024
	ds_read_b128 v[138:141], v142 offset:2048
	ds_read_b128 v[142:145], v142 offset:3072
	s_add_u32 s26, s46, 0x40000
	s_addc_u32 s27, s47, 0
	s_mov_b32 m0, s81
	v_lshl_add_u64 v[226:227], s[26:27], 0, v[150:151]
	ds_read_b128 v[178:181], v201 offset:32768
	ds_read_b128 v[182:185], v201 offset:33792
	ds_read_b128 v[186:189], v201 offset:34816
	ds_read_b128 v[202:205], v201 offset:35840
	ds_read_b128 v[206:209], v201 offset:36864
	ds_read_b128 v[214:217], v201 offset:37888
	ds_read_b128 v[218:221], v201 offset:38912
	ds_read_b128 v[222:225], v201 offset:39936
	global_load_lds_dwordx4 v[226:227], off
	s_mov_b32 m0, s82
	v_lshl_add_u64 v[226:227], s[26:27], 0, v[148:149]
	global_load_lds_dwordx4 v[226:227], off
	s_waitcnt lgkmcnt(8)
	s_barrier
; #define PG8_STAGE(bufoff, gbase, voff) do { _Pragma("unroll") for (int _i = 0; _i < 2; ++_i) \
;         __builtin_amdgcn_global_load_lds((const unsigned*)((const char*)(gbase) + (voff)[_i]), (LAS unsigned*)(lds + (bufoff) + ldsw + _i * 8192), 16, 0, 0); } while (0)
; #define PG8_LDA(dst, b, h) do { _Pragma("unroll") for (int m = 0; m < 4; ++m) _Pragma("unroll") for (int k = 0; k < 2; ++k) dst[m][k] = *(const LAS bf16x8*)(lds + PG8_SA(b, h) + aoff + m * 2048 + k * 1024); } while (0)
; #define PG8_LDB(dst, b, h) do { _Pragma("unroll") for (int n = 0; n < 2; ++n) _Pragma("unroll") for (int k = 0; k < 2; ++k) dst[n][k] = *(const LAS bf16x8*)(lds + PG8_SB(b, h) + boff + n * 2048 + k * 1024); } while (0)
; #define PG8_MMA(ai, bj, At, Bt) do { __builtin_amdgcn_s_setprio(1); _Pragma("unroll") for (int m = 0; m < 4; ++m) _Pragma("unroll") for (int n = 0; n < 2; ++n) _Pragma("unroll") for (int k = 0; k < 2; ++k) \
;         acc[ai][bj][m][n] = __builtin_amdgcn_mfma_f32_16x16x32_bf16(Bt[n][k], At[m][k], acc[ai][bj][m][n], 0, 0, 0); __builtin_amdgcn_s_setprio(0); } while (0)
; #define PG8_WAIT_V(n) asm volatile("s_waitcnt vmcnt(" #n ")" ::: "memory")
; #define PG8_WAIT_L(n) asm volatile("s_waitcnt lgkmcnt(" #n ")" ::: "memory")
; #define PG8_BAR __builtin_amdgcn_s_barrier()
; #define PG8_SCHED __builtin_amdgcn_sched_barrier(0)
; template <class Epi>
; DEVI void gemm_phase(LAS unsigned char* lds, const Gemm g, const Epi& E) {
;     ...
;             PG8_BAR; PG8_WAIT_L(0); PG8_MMA(1, 0, At, B0); PG8_BAR; PG8_SCHED;
;             PG8_STAGE(PG8_SB(0, 1), b2 + hstepB, voffB);
;             PG8_WAIT_V(6); PG8_BAR; PG8_MMA(1, 1, At, B1); PG8_BAR;
;             PG8_LDB(B0, 1, 0); PG8_SCHED; PG8_LDA(At, 1, 0); PG8_STAGE(PG8_SA(0, 1), a2 + hstepA, voffA);
;             PG8_WAIT_L(8); PG8_BAR; PG8_WAIT_L(0); PG8_MMA(0, 0, At, B0); PG8_BAR; PG8_SCHED;
;             PG8_LDB(B1, 1, 1); PG8_STAGE(PG8_SB(1, 0), b3, voffB);
;             PG8_BAR; PG8_WAIT_L(0); PG8_MMA(0, 1, At, B1); PG8_BAR;
;             PG8_LDA(At, 1, 1); PG8_STAGE(PG8_SA(1, 0), a3, voffA);
;             PG8_BAR; PG8_WAIT_L(0); PG8_MMA(1, 0, At, B0); PG8_BAR; PG8_SCHED;
;             PG8_STAGE(PG8_SB(1, 1), b3 + hstepB, voffB);
;             PG8_WAIT_V(6); PG8_BAR; PG8_MMA(1, 1, At, B1); PG8_BAR;
;         }
	s_waitcnt lgkmcnt(0)
	v_mfma_f32_16x16x32_bf16 v[126:129], v[130:133], v[178:181], v[126:129]
	v_mfma_f32_16x16x32_bf16 v[122:125], v[138:141], v[178:181], v[122:125]
	v_mfma_f32_16x16x32_bf16 v[110:113], v[130:133], v[186:189], v[110:113]
	v_mfma_f32_16x16x32_bf16 v[106:109], v[138:141], v[186:189], v[106:109]
	v_mfma_f32_16x16x32_bf16 v[94:97], v[130:133], v[206:209], v[94:97]
	v_mfma_f32_16x16x32_bf16 v[90:93], v[138:141], v[206:209], v[90:93]
	v_mfma_f32_16x16x32_bf16 v[78:81], v[130:133], v[218:221], v[78:81]
	v_mfma_f32_16x16x32_bf16 v[74:77], v[138:141], v[218:221], v[74:77]
	v_mfma_f32_16x16x32_bf16 v[126:129], v[134:137], v[182:185], v[126:129]
	v_mfma_f32_16x16x32_bf16 v[122:125], v[142:145], v[182:185], v[122:125]
	v_mfma_f32_16x16x32_bf16 v[110:113], v[134:137], v[202:205], v[110:113]
	v_mfma_f32_16x16x32_bf16 v[106:109], v[142:145], v[202:205], v[106:109]
	v_mfma_f32_16x16x32_bf16 v[94:97], v[134:137], v[214:217], v[94:97]
	v_mfma_f32_16x16x32_bf16 v[90:93], v[142:145], v[214:217], v[90:93]
	v_mfma_f32_16x16x32_bf16 v[78:81], v[134:137], v[222:225], v[78:81]
	v_mfma_f32_16x16x32_bf16 v[74:77], v[142:145], v[222:225], v[74:77]
	s_barrier
	s_add_i32 s39, 0, 0x1c000
	s_add_i32 s26, s38, s78
	v_add_u32_e32 v192, s39, v197
	v_lshl_add_u64 v[162:163], v[162:163], 0, s[70:71]
	s_mov_b32 m0, s26
	ds_read_b128 v[226:229], v192
	ds_read_b128 v[230:233], v192 offset:1024
	ds_read_b128 v[234:237], v192 offset:2048
	ds_read_b128 v[238:241], v192 offset:3072
	global_load_lds_dwordx4 v[162:163], off
	s_add_i32 m0, s26, 0x2000
	v_lshl_add_u64 v[162:163], v[164:165], 0, s[70:71]
	global_load_lds_dwordx4 v[162:163], off
	s_barrier
	s_waitcnt lgkmcnt(0)
	v_mfma_f32_16x16x32_bf16 v[118:121], v[226:229], v[178:181], v[118:121]
	v_mfma_f32_16x16x32_bf16 v[114:117], v[234:237], v[178:181], v[114:117]
	v_mfma_f32_16x16x32_bf16 v[102:105], v[226:229], v[186:189], v[102:105]
	v_mfma_f32_16x16x32_bf16 v[98:101], v[234:237], v[186:189], v[98:101]
	v_mfma_f32_16x16x32_bf16 v[86:89], v[226:229], v[206:209], v[86:89]
	v_mfma_f32_16x16x32_bf16 v[82:85], v[234:237], v[206:209], v[82:85]
	v_mfma_f32_16x16x32_bf16 v[70:73], v[226:229], v[218:221], v[70:73]
	v_mfma_f32_16x16x32_bf16 v[66:69], v[234:237], v[218:221], v[66:69]
	v_mfma_f32_16x16x32_bf16 v[118:121], v[230:233], v[182:185], v[118:121]
	v_mfma_f32_16x16x32_bf16 v[114:117], v[238:241], v[182:185], v[114:117]
	v_mfma_f32_16x16x32_bf16 v[102:105], v[230:233], v[202:205], v[102:105]
	v_mfma_f32_16x16x32_bf16 v[98:101], v[238:241], v[202:205], v[98:101]
	v_mfma_f32_16x16x32_bf16 v[86:89], v[230:233], v[214:217], v[86:89]
	v_mfma_f32_16x16x32_bf16 v[82:85], v[238:241], v[214:217], v[82:85]
	v_mfma_f32_16x16x32_bf16 v[70:73], v[230:233], v[222:225], v[70:73]
	v_mfma_f32_16x16x32_bf16 v[66:69], v[238:241], v[222:225], v[66:69]
	s_mov_b32 m0, s83
	v_lshl_add_u64 v[162:163], v[190:191], 0, s[70:71]
	s_barrier
	ds_read_b128 v[178:181], v201 offset:49152
	ds_read_b128 v[182:185], v201 offset:50176
	ds_read_b128 v[186:189], v201 offset:51200
	ds_read_b128 v[202:205], v201 offset:52224
	ds_read_b128 v[206:209], v201 offset:53248
	ds_read_b128 v[214:217], v201 offset:54272
	ds_read_b128 v[218:221], v201 offset:55296
	ds_read_b128 v[222:225], v201 offset:56320
	global_load_lds_dwordx4 v[162:163], off
	s_mov_b32 m0, s84
	v_lshl_add_u64 v[162:163], v[194:195], 0, s[70:71]
	global_load_lds_dwordx4 v[162:163], off
	s_barrier
	s_waitcnt lgkmcnt(0)
	v_mfma_f32_16x16x32_bf16 v[50:53], v[130:133], v[178:181], v[50:53]
	v_mfma_f32_16x16x32_bf16 v[54:57], v[138:141], v[178:181], v[54:57]
	v_mfma_f32_16x16x32_bf16 v[34:37], v[130:133], v[186:189], v[34:37]
	v_mfma_f32_16x16x32_bf16 v[38:41], v[138:141], v[186:189], v[38:41]
	v_mfma_f32_16x16x32_bf16 v[18:21], v[130:133], v[206:209], v[18:21]
	v_mfma_f32_16x16x32_bf16 v[22:25], v[138:141], v[206:209], v[22:25]
	v_mfma_f32_16x16x32_bf16 v[0:3], v[130:133], v[218:221], v[0:3]
	v_mfma_f32_16x16x32_bf16 v[4:7], v[138:141], v[218:221], v[4:7]
	v_mfma_f32_16x16x32_bf16 v[50:53], v[134:137], v[182:185], v[50:53]
	v_mfma_f32_16x16x32_bf16 v[54:57], v[142:145], v[182:185], v[54:57]
	v_mfma_f32_16x16x32_bf16 v[34:37], v[134:137], v[202:205], v[34:37]
	v_mfma_f32_16x16x32_bf16 v[38:41], v[142:145], v[202:205], v[38:41]
	v_mfma_f32_16x16x32_bf16 v[18:21], v[134:137], v[214:217], v[18:21]
	v_mfma_f32_16x16x32_bf16 v[22:25], v[142:145], v[214:217], v[22:25]
	v_mfma_f32_16x16x32_bf16 v[0:3], v[134:137], v[222:225], v[0:3]
	v_mfma_f32_16x16x32_bf16 v[4:7], v[142:145], v[222:225], v[4:7]
	s_barrier
	s_add_u32 s26, s36, 0x40080
	s_addc_u32 s27, s37, 0
	s_add_i32 s36, s39, s78
	s_mov_b32 m0, s36
	v_lshl_add_u64 v[130:131], s[26:27], 0, v[8:9]
	global_load_lds_dwordx4 v[130:131], off
	s_add_i32 m0, s36, 0x2000
	v_lshl_add_u64 v[130:131], s[26:27], 0, v[146:147]
	global_load_lds_dwordx4 v[130:131], off
	s_waitcnt vmcnt(6)
	s_barrier
	v_mfma_f32_16x16x32_bf16 v[58:61], v[226:229], v[178:181], v[58:61]
	v_mfma_f32_16x16x32_bf16 v[62:65], v[234:237], v[178:181], v[62:65]
	v_mfma_f32_16x16x32_bf16 v[42:45], v[226:229], v[186:189], v[42:45]
	v_mfma_f32_16x16x32_bf16 v[46:49], v[234:237], v[186:189], v[46:49]
	v_mfma_f32_16x16x32_bf16 v[26:29], v[226:229], v[206:209], v[26:29]
	v_mfma_f32_16x16x32_bf16 v[30:33], v[234:237], v[206:209], v[30:33]
	v_mfma_f32_16x16x32_bf16 v[10:13], v[226:229], v[218:221], v[10:13]
	v_mfma_f32_16x16x32_bf16 v[14:17], v[234:237], v[218:221], v[14:17]
	v_mfma_f32_16x16x32_bf16 v[58:61], v[230:233], v[182:185], v[58:61]
	v_mfma_f32_16x16x32_bf16 v[62:65], v[238:241], v[182:185], v[62:65]
	v_mfma_f32_16x16x32_bf16 v[42:45], v[230:233], v[202:205], v[42:45]
	v_mfma_f32_16x16x32_bf16 v[46:49], v[238:241], v[202:205], v[46:49]
	v_mfma_f32_16x16x32_bf16 v[26:29], v[230:233], v[214:217], v[26:29]
	v_mfma_f32_16x16x32_bf16 v[30:33], v[238:241], v[214:217], v[30:33]
	v_mfma_f32_16x16x32_bf16 v[10:13], v[230:233], v[222:225], v[10:13]
	v_mfma_f32_16x16x32_bf16 v[14:17], v[238:241], v[222:225], v[14:17]
	s_add_i32 s19, s19, 2
	s_add_u32 s16, s16, 0x100
	s_addc_u32 s17, s17, 0
	s_add_u32 s9, s9, 0x100
	s_addc_u32 s18, s18, 0
	s_cmp_gt_u32 s19, 13
	s_barrier
; template <class Epi>
; DEVI void gemm_phase(LAS unsigned char* lds, const Gemm g, const Epi& E) {
;     ...
;             const int row0 = cur.pm * BM + wr * 64 + fr, col0 = cur.pn * BM + wc * 32 + (Epi::PERM ? 8 : 4) * fq; constexpr int NST = Epi::PERM ? 4 : 16;
;             float rsv[8];
;             if constexpr (Epi::RS) { f32x4 q4[8];
; #pragma unroll
;                 for (int i = 0; i < 8; ++i) q4[i] = *(const f32x4*)(E.ssq_in + (size_t)(row0 + (i >> 2) * HALF + (i & 3) * 16) * 4);
; #pragma unroll
;                 for (int i = 0; i < 8; ++i) rsv[i] = rsqrtf((((q4[i][0] + q4[i][1]) + q4[i][2]) + q4[i][3]) * (1.f / DM) + 1e-6f); }
	s_cbranch_scc0 .LBB0_1672
	v_lshlrev_b32_e32 v213, 4, v193
	v_add_u32_e32 v213, 0x21000, v213
	s_setprio 0
	v_lshl_add_u32 v194, s4, 8, v193
	v_add_u32_e32 v178, 0xb0, v194
	v_ashrrev_i32_e32 v195, 31, v194
	v_or_b32_e32 v190, 16, v194
	v_ashrrev_i32_e32 v179, 31, v178
	v_lshl_add_u64 v[130:131], v[194:195], 4, s[10:11]
	v_ashrrev_i32_e32 v191, 31, v190
	v_lshl_add_u64 v[134:135], v[178:179], 4, s[10:11]
	ds_read_b128 v[202:205], v213
	v_or_b32_e32 v188, 32, v194
	ds_read_b128 v[134:137], v213 offset:2816
	v_lshl_add_u64 v[130:131], v[190:191], 4, s[10:11]
	ds_read_b128 v[206:209], v213 offset:256
	v_ashrrev_i32_e32 v189, 31, v188
	v_or_b32_e32 v186, 48, v194
	v_lshl_add_u64 v[130:131], v[188:189], 4, s[10:11]
	v_ashrrev_i32_e32 v187, 31, v186
	ds_read_b128 v[214:217], v213 offset:512
	v_lshl_add_u64 v[130:131], v[186:187], 4, s[10:11]
	ds_read_b128 v[218:221], v213 offset:768
	v_add_u32_e32 v184, 0x80, v194
	v_ashrrev_i32_e32 v185, 31, v184
	v_add_u32_e32 v182, 0x90, v194
	v_lshl_add_u64 v[130:131], v[184:185], 4, s[10:11]
	v_ashrrev_i32_e32 v183, 31, v182
	ds_read_b128 v[138:141], v213 offset:2048
	v_lshl_add_u64 v[130:131], v[182:183], 4, s[10:11]
	v_add_u32_e32 v180, 0xa0, v194
	ds_read_b128 v[142:145], v213 offset:2304
	v_ashrrev_i32_e32 v181, 31, v180
	v_lshl_add_u64 v[130:131], v[180:181], 4, s[10:11]
	ds_read_b128 v[130:133], v213 offset:2560
	s_mov_b32 s0, 0x358637bd
	s_mov_b64 s[36:37], s[14:15]
	s_mov_b64 s[16:17], s[12:13]
	s_waitcnt lgkmcnt(0)
	v_mov_b32_e32 v163, v202
	v_mov_b32_e32 v165, v204
	v_mov_b32_e32 v162, v206
	v_mov_b32_e32 v202, v207
	v_pk_add_f32 v[162:163], v[162:163], v[202:203]
	v_mov_b32_e32 v164, v208
	v_pk_add_f32 v[162:163], v[164:165], v[162:163]
	v_mov_b32_e32 v204, v209
	v_pk_add_f32 v[162:163], v[204:205], v[162:163]
	v_mov_b64_e32 v[202:203], s[0:1]
	v_pk_fma_f32 v[162:163], v[162:163], s[72:73], v[202:203] op_sel_hi:[1,0,0]
	v_mov_b32_e32 v165, v216
	v_mul_f32_e32 v164, 0x4b800000, v163
	v_cmp_gt_f32_e64 s[4:5], s94, v163
	v_cmp_gt_f32_e32 vcc, s94, v162
	v_mov_b32_e32 v216, v221
	v_cndmask_b32_e64 v163, v163, v164, s[4:5]
	v_rsq_f32_e32 v163, v163
	s_nop 0
	v_mul_f32_e32 v164, 0x45800000, v163
	v_cndmask_b32_e64 v200, v163, v164, s[4:5]
	v_mul_f32_e32 v163, 0x4b800000, v162
	v_cndmask_b32_e32 v162, v162, v163, vcc
	v_rsq_f32_e32 v162, v162
	v_mov_b32_e32 v164, v220
	v_pk_mul_f32 v[126:127], v[126:127], v[200:201] op_sel_hi:[1,0]
	v_pk_mul_f32 v[122:123], v[122:123], v[200:201] op_sel_hi:[1,0]
	v_mul_f32_e32 v163, 0x45800000, v162
	v_cndmask_b32_e32 v198, v162, v163, vcc
	v_mov_b32_e32 v162, v218
	v_mov_b32_e32 v163, v214
	v_mov_b32_e32 v214, v219
	v_pk_add_f32 v[162:163], v[162:163], v[214:215]
	v_pk_mul_f32 v[118:119], v[118:119], v[200:201] op_sel_hi:[1,0]
	v_pk_add_f32 v[162:163], v[164:165], v[162:163]
	v_pk_mul_f32 v[124:125], v[124:125], v[200:201] op_sel_hi:[1,0]
	v_pk_add_f32 v[162:163], v[216:217], v[162:163]
	v_pk_mul_f32 v[114:115], v[114:115], v[200:201] op_sel_hi:[1,0]
	v_pk_fma_f32 v[162:163], v[162:163], s[72:73], v[202:203] op_sel_hi:[1,0,0]
	v_pk_mul_f32 v[128:129], v[128:129], v[200:201] op_sel_hi:[1,0]
	v_mul_f32_e32 v164, 0x4b800000, v163
	v_cmp_gt_f32_e64 s[4:5], s94, v163
	v_cmp_gt_f32_e32 vcc, s94, v162
	v_pk_mul_f32 v[120:121], v[120:121], v[200:201] op_sel_hi:[1,0]
	v_cndmask_b32_e64 v163, v163, v164, s[4:5]
	v_rsq_f32_e32 v163, v163
	v_pk_mul_f32 v[116:117], v[116:117], v[200:201] op_sel_hi:[1,0]
	v_pk_mul_f32 v[106:107], v[106:107], v[198:199] op_sel_hi:[1,0]
	v_pk_mul_f32 v[110:111], v[110:111], v[198:199] op_sel_hi:[1,0]
	v_mul_f32_e32 v164, 0x45800000, v163
	v_cndmask_b32_e64 v196, v163, v164, s[4:5]
	v_mul_f32_e32 v163, 0x4b800000, v162
	v_cndmask_b32_e32 v162, v162, v163, vcc
	v_rsq_f32_e32 v162, v162
	v_pk_mul_f32 v[102:103], v[102:103], v[198:199] op_sel_hi:[1,0]
	v_pk_mul_f32 v[108:109], v[108:109], v[198:199] op_sel_hi:[1,0]
	v_pk_mul_f32 v[98:99], v[98:99], v[198:199] op_sel_hi:[1,0]
	v_mul_f32_e32 v163, 0x45800000, v162
	v_cndmask_b32_e32 v192, v162, v163, vcc
	v_mov_b32_e32 v162, v142
	v_mov_b32_e32 v163, v138
	v_mov_b32_e32 v138, v143
	v_pk_add_f32 v[138:139], v[162:163], v[138:139]
	v_mov_b32_e32 v142, v144
	v_mov_b32_e32 v143, v140
	v_pk_add_f32 v[138:139], v[142:143], v[138:139]
	v_mov_b32_e32 v142, v134
	v_mov_b32_e32 v143, v130
	v_mov_b32_e32 v130, v135
	v_pk_add_f32 v[130:131], v[142:143], v[130:131]
	v_mov_b32_e32 v134, v136
	v_mov_b32_e32 v135, v132
	v_pk_add_f32 v[130:131], v[134:135], v[130:131]
	v_mov_b32_e32 v132, v137
	v_pk_add_f32 v[130:131], v[132:133], v[130:131]
	v_mul_f32_e32 v133, 0xbfb8aa3b, v126
	v_exp_f32_e32 v133, v133
	v_mov_b32_e32 v140, v145
	v_pk_add_f32 v[138:139], v[140:141], v[138:139]
	v_pk_fma_f32 v[130:131], v[130:131], s[72:73], v[202:203] op_sel_hi:[1,0,0]
	v_add_f32_e32 v133, 1.0, v133
	v_rcp_f32_e32 v136, v133
	v_mul_f32_e32 v133, 0xbfb8aa3b, v122
	v_exp_f32_e32 v133, v133
	v_pk_fma_f32 v[138:139], v[138:139], s[72:73], v[202:203] op_sel_hi:[1,0,0]
	v_mul_f32_e32 v132, 0x4b800000, v131
	v_mul_f32_e32 v140, 0x4b800000, v139
	v_add_f32_e32 v133, 1.0, v133
	v_rcp_f32_e32 v142, v133
	v_mul_f32_e32 v133, 0xbfb8aa3b, v127
	v_exp_f32_e32 v133, v133
	v_cmp_gt_f32_e64 s[4:5], s94, v139
	v_cmp_gt_f32_e32 vcc, s94, v138
	v_pk_mul_f32 v[112:113], v[112:113], v[198:199] op_sel_hi:[1,0]
	v_add_f32_e32 v133, 1.0, v133
	v_rcp_f32_e32 v137, v133
	v_cndmask_b32_e64 v139, v139, v140, s[4:5]
	v_rsq_f32_e32 v139, v139
	v_pk_mul_f32 v[104:105], v[104:105], v[198:199] op_sel_hi:[1,0]
	v_pk_mul_f32 v[126:127], v[126:127], v[136:137]
	v_pk_mul_f32 v[100:101], v[100:101], v[198:199] op_sel_hi:[1,0]
	v_pk_mul_f32 v[118:119], v[118:119], v[126:127]
; template <class Epi>
; DEVI void gemm_phase(LAS unsigned char* lds, const Gemm g, const Epi& E) {
;     ...
;                 for (int mm = 0; mm < 2; ++mm) {
;                     const int m = m0 + mm;
;                     const int r = row0 + ai * HALF + m * 16; float rs = 1.f, part = 0.f;
;                     if constexpr (Epi::RS) rs = rsv[ai * 4 + m];
;                     if constexpr (Epi::PAIR) E.pair8(cur.b, r, cur.pn * HALF + wc * 32 + 8 * fq, acc[ai][0][m][0] * rs, acc[ai][0][m][1] * rs, acc[ai][1][m][0] * rs, acc[ai][1][m][1] * rs);
	v_mul_f32_e32 v126, 0xbfb8aa3b, v123
	v_exp_f32_e32 v126, v126
	v_mul_f32_e32 v140, 0x45800000, v139
	v_cndmask_b32_e64 v140, v139, v140, s[4:5]
	v_mul_f32_e32 v139, 0x4b800000, v138
	v_add_f32_e32 v126, 1.0, v126
	v_rcp_f32_e32 v143, v126
	v_cmp_gt_f32_e64 s[4:5], s94, v131
	v_cndmask_b32_e32 v138, v138, v139, vcc
	v_rsq_f32_e32 v138, v138
	v_pk_mul_f32 v[122:123], v[122:123], v[142:143]
	v_cndmask_b32_e64 v131, v131, v132, s[4:5]
	v_pk_mul_f32 v[122:123], v[114:115], v[122:123]
	v_mul_f32_e32 v115, 0xbfb8aa3b, v124
	v_exp_f32_e32 v115, v115
	v_mul_f32_e32 v114, 0xbfb8aa3b, v128
	v_exp_f32_e32 v114, v114
	v_rsq_f32_e32 v131, v131
	v_add_f32_e32 v115, 1.0, v115
	v_rcp_f32_e32 v126, v115
	v_mul_f32_e32 v115, 0xbfb8aa3b, v129
	v_exp_f32_e32 v115, v115
	v_add_f32_e32 v114, 1.0, v114
	v_rcp_f32_e32 v114, v114
	v_mul_f32_e32 v139, 0x45800000, v138
	v_add_f32_e32 v115, 1.0, v115
	v_rcp_f32_e32 v115, v115
	v_mul_f32_e32 v132, 0x45800000, v131
	v_cndmask_b32_e32 v138, v138, v139, vcc
	v_cmp_gt_f32_e32 vcc, s94, v130
	v_pk_mul_f32 v[114:115], v[128:129], v[114:115]
	v_cndmask_b32_e64 v134, v131, v132, s[4:5]
	v_pk_mul_f32 v[120:121], v[120:121], v[114:115]
	v_mul_f32_e32 v114, 0xbfb8aa3b, v125
	v_exp_f32_e32 v114, v114
	v_mul_f32_e32 v131, 0x4b800000, v130
	v_cndmask_b32_e32 v130, v130, v131, vcc
	v_rsq_f32_e32 v130, v130
	v_add_f32_e32 v114, 1.0, v114
	v_rcp_f32_e32 v127, v114
	v_pk_mul_f32 v[90:91], v[90:91], v[196:197] op_sel_hi:[1,0]
	v_mul_f32_e32 v131, 0x45800000, v130
	v_cndmask_b32_e32 v132, v130, v131, vcc
	v_lshl_or_b32 v130, s86, 7, v199
	v_ashrrev_i32_e32 v131, 31, v130
	v_pk_mul_f32 v[114:115], v[124:125], v[126:127]
	v_lshl_add_u64 v[130:131], v[130:131], 1, s[28:29]
	v_pk_mul_f32 v[124:125], v[116:117], v[114:115]
	v_cvt_pk_bf16_f32 v114, v118, v119
	v_cvt_pk_bf16_f32 v115, v120, v121
	v_cvt_pk_bf16_f32 v116, v122, v123
	v_cvt_pk_bf16_f32 v117, v124, v125
	v_mad_i64_i32 v[118:119], s[0:1], v194, s35, v[130:131]
	global_store_dwordx4 v[118:119], v[114:117], off
	v_pk_mul_f32 v[94:95], v[94:95], v[196:197] op_sel_hi:[1,0]
	v_pk_mul_f32 v[86:87], v[86:87], v[196:197] op_sel_hi:[1,0]
	v_mul_f32_e32 v115, 0xbfb8aa3b, v106
	v_exp_f32_e32 v115, v115
	v_mul_f32_e32 v114, 0xbfb8aa3b, v110
	v_exp_f32_e32 v114, v114
	v_pk_mul_f32 v[92:93], v[92:93], v[196:197] op_sel_hi:[1,0]
	v_add_f32_e32 v115, 1.0, v115
	v_rcp_f32_e32 v116, v115
	v_mul_f32_e32 v115, 0xbfb8aa3b, v111
	v_exp_f32_e32 v115, v115
	v_add_f32_e32 v114, 1.0, v114
	v_rcp_f32_e32 v114, v114
	v_pk_mul_f32 v[82:83], v[82:83], v[196:197] op_sel_hi:[1,0]
	v_add_f32_e32 v115, 1.0, v115
	v_rcp_f32_e32 v115, v115
	v_pk_mul_f32 v[96:97], v[96:97], v[196:197] op_sel_hi:[1,0]
	v_pk_mul_f32 v[88:89], v[88:89], v[196:197] op_sel_hi:[1,0]
	v_pk_mul_f32 v[84:85], v[84:85], v[196:197] op_sel_hi:[1,0]
	v_pk_mul_f32 v[110:111], v[110:111], v[114:115]
	v_pk_mul_f32 v[74:75], v[74:75], v[192:193] op_sel_hi:[1,0]
	v_pk_mul_f32 v[102:103], v[102:103], v[110:111]
	v_mul_f32_e32 v110, 0xbfb8aa3b, v107
	v_exp_f32_e32 v110, v110
	v_pk_mul_f32 v[78:79], v[78:79], v[192:193] op_sel_hi:[1,0]
	v_pk_mul_f32 v[70:71], v[70:71], v[192:193] op_sel_hi:[1,0]
	v_pk_mul_f32 v[76:77], v[76:77], v[192:193] op_sel_hi:[1,0]
	v_add_f32_e32 v110, 1.0, v110
	v_rcp_f32_e32 v117, v110
	v_pk_mul_f32 v[66:67], v[66:67], v[192:193] op_sel_hi:[1,0]
	v_pk_mul_f32 v[80:81], v[80:81], v[192:193] op_sel_hi:[1,0]
	v_pk_mul_f32 v[72:73], v[72:73], v[192:193] op_sel_hi:[1,0]
	v_pk_mul_f32 v[106:107], v[106:107], v[116:117]
	v_pk_mul_f32 v[68:69], v[68:69], v[192:193] op_sel_hi:[1,0]
	v_pk_mul_f32 v[106:107], v[98:99], v[106:107]
	v_mul_f32_e32 v99, 0xbfb8aa3b, v108
	v_exp_f32_e32 v99, v99
	v_mul_f32_e32 v98, 0xbfb8aa3b, v112
	v_exp_f32_e32 v98, v98
	v_pk_mul_f32 v[54:55], v[54:55], v[140:141] op_sel_hi:[1,0]
	v_add_f32_e32 v99, 1.0, v99
	v_rcp_f32_e32 v110, v99
	v_mul_f32_e32 v99, 0xbfb8aa3b, v113
	v_exp_f32_e32 v99, v99
	v_add_f32_e32 v98, 1.0, v98
	v_rcp_f32_e32 v98, v98
	v_pk_mul_f32 v[50:51], v[50:51], v[140:141] op_sel_hi:[1,0]
	v_add_f32_e32 v99, 1.0, v99
	v_rcp_f32_e32 v99, v99
	v_pk_mul_f32 v[58:59], v[58:59], v[140:141] op_sel_hi:[1,0]
	v_pk_mul_f32 v[56:57], v[56:57], v[140:141] op_sel_hi:[1,0]
	v_pk_mul_f32 v[52:53], v[52:53], v[140:141] op_sel_hi:[1,0]
	v_pk_mul_f32 v[98:99], v[112:113], v[98:99]
	v_pk_mul_f32 v[62:63], v[62:63], v[140:141] op_sel_hi:[1,0]
	v_pk_mul_f32 v[104:105], v[104:105], v[98:99]
	v_mul_f32_e32 v98, 0xbfb8aa3b, v109
	v_exp_f32_e32 v98, v98
	v_pk_mul_f32 v[60:61], v[60:61], v[140:141] op_sel_hi:[1,0]
	v_pk_mul_f32 v[64:65], v[64:65], v[140:141] op_sel_hi:[1,0]
	v_pk_mul_f32 v[38:39], v[38:39], v[138:139] op_sel_hi:[1,0]
	v_add_f32_e32 v98, 1.0, v98
	v_rcp_f32_e32 v111, v98
	v_pk_mul_f32 v[34:35], v[34:35], v[138:139] op_sel_hi:[1,0]
	v_pk_mul_f32 v[42:43], v[42:43], v[138:139] op_sel_hi:[1,0]
	v_pk_mul_f32 v[40:41], v[40:41], v[138:139] op_sel_hi:[1,0]
	v_pk_mul_f32 v[98:99], v[108:109], v[110:111]
	v_pk_mul_f32 v[36:37], v[36:37], v[138:139] op_sel_hi:[1,0]
	v_pk_mul_f32 v[108:109], v[100:101], v[98:99]
	v_cvt_pk_bf16_f32 v98, v102, v103
	v_cvt_pk_bf16_f32 v99, v104, v105
	v_cvt_pk_bf16_f32 v100, v106, v107
	v_cvt_pk_bf16_f32 v101, v108, v109
	v_mad_i64_i32 v[102:103], s[0:1], v190, s35, v[130:131]
	global_store_dwordx4 v[102:103], v[98:101], off
	v_pk_mul_f32 v[46:47], v[46:47], v[138:139] op_sel_hi:[1,0]
	v_pk_mul_f32 v[44:45], v[44:45], v[138:139] op_sel_hi:[1,0]
	v_mul_f32_e32 v99, 0xbfb8aa3b, v90
	v_exp_f32_e32 v99, v99
	v_mul_f32_e32 v98, 0xbfb8aa3b, v94
	v_exp_f32_e32 v98, v98
	v_pk_mul_f32 v[48:49], v[48:49], v[138:139] op_sel_hi:[1,0]
	v_add_f32_e32 v99, 1.0, v99
	v_rcp_f32_e32 v100, v99
; template <class Epi>
; DEVI void gemm_phase(LAS unsigned char* lds, const Gemm g, const Epi& E) {
;     ...
;                     if constexpr (Epi::PAIR) E.pair8(cur.b, r, cur.pn * HALF + wc * 32 + 8 * fq, acc[ai][0][m][0] * rs, acc[ai][0][m][1] * rs, acc[ai][1][m][0] * rs, acc[ai][1][m][1] * rs);
	v_mul_f32_e32 v99, 0xbfb8aa3b, v95
	v_exp_f32_e32 v99, v99
	v_add_f32_e32 v98, 1.0, v98
	v_rcp_f32_e32 v98, v98
	v_pk_mul_f32 v[22:23], v[22:23], v[134:135] op_sel_hi:[1,0]
	v_add_f32_e32 v99, 1.0, v99
	v_rcp_f32_e32 v99, v99
	v_pk_mul_f32 v[18:19], v[18:19], v[134:135] op_sel_hi:[1,0]
	v_pk_mul_f32 v[26:27], v[26:27], v[134:135] op_sel_hi:[1,0]
	v_pk_mul_f32 v[24:25], v[24:25], v[134:135] op_sel_hi:[1,0]
	v_pk_mul_f32 v[94:95], v[94:95], v[98:99]
	v_pk_mul_f32 v[20:21], v[20:21], v[134:135] op_sel_hi:[1,0]
	v_pk_mul_f32 v[86:87], v[86:87], v[94:95]
	v_mul_f32_e32 v94, 0xbfb8aa3b, v91
	v_exp_f32_e32 v94, v94
	v_pk_mul_f32 v[30:31], v[30:31], v[134:135] op_sel_hi:[1,0]
	v_pk_mul_f32 v[28:29], v[28:29], v[134:135] op_sel_hi:[1,0]
	v_pk_mul_f32 v[32:33], v[32:33], v[134:135] op_sel_hi:[1,0]
	v_add_f32_e32 v94, 1.0, v94
	v_rcp_f32_e32 v101, v94
	v_pk_mul_f32 v[4:5], v[4:5], v[132:133] op_sel_hi:[1,0]
	v_pk_mul_f32 v[0:1], v[0:1], v[132:133] op_sel_hi:[1,0]
	v_pk_mul_f32 v[10:11], v[10:11], v[132:133] op_sel_hi:[1,0]
	v_pk_mul_f32 v[90:91], v[90:91], v[100:101]
	v_pk_mul_f32 v[6:7], v[6:7], v[132:133] op_sel_hi:[1,0]
	v_pk_mul_f32 v[90:91], v[82:83], v[90:91]
	v_mul_f32_e32 v83, 0xbfb8aa3b, v92
	v_exp_f32_e32 v83, v83
	v_mul_f32_e32 v82, 0xbfb8aa3b, v96
	v_exp_f32_e32 v82, v82
	v_pk_mul_f32 v[2:3], v[2:3], v[132:133] op_sel_hi:[1,0]
	v_add_f32_e32 v83, 1.0, v83
	v_rcp_f32_e32 v94, v83
	v_mul_f32_e32 v83, 0xbfb8aa3b, v97
	v_exp_f32_e32 v83, v83
	v_add_f32_e32 v82, 1.0, v82
	v_rcp_f32_e32 v82, v82
	v_pk_mul_f32 v[14:15], v[14:15], v[132:133] op_sel_hi:[1,0]
	v_add_f32_e32 v83, 1.0, v83
	v_rcp_f32_e32 v83, v83
	v_pk_mul_f32 v[12:13], v[12:13], v[132:133] op_sel_hi:[1,0]
	v_pk_mul_f32 v[16:17], v[16:17], v[132:133] op_sel_hi:[1,0]
	s_and_b64 vcc, exec, s[2:3]
	v_pk_mul_f32 v[82:83], v[96:97], v[82:83]
	s_mov_b32 s86, s8
	v_pk_mul_f32 v[88:89], v[88:89], v[82:83]
	v_mul_f32_e32 v82, 0xbfb8aa3b, v93
	v_exp_f32_e32 v82, v82
	s_mov_b32 s4, s6
	v_add_f32_e32 v82, 1.0, v82
	v_rcp_f32_e32 v95, v82
	s_nop 0
	v_pk_mul_f32 v[82:83], v[92:93], v[94:95]
	s_nop 0
	v_pk_mul_f32 v[92:93], v[84:85], v[82:83]
	v_cvt_pk_bf16_f32 v82, v86, v87
	v_cvt_pk_bf16_f32 v83, v88, v89
	v_cvt_pk_bf16_f32 v84, v90, v91
	v_cvt_pk_bf16_f32 v85, v92, v93
	v_mad_i64_i32 v[86:87], s[0:1], v188, s35, v[130:131]
	global_store_dwordx4 v[86:87], v[82:85], off
	s_nop 1
	v_mul_f32_e32 v83, 0xbfb8aa3b, v74
	v_exp_f32_e32 v83, v83
	v_mul_f32_e32 v82, 0xbfb8aa3b, v78
	v_exp_f32_e32 v82, v82
	v_add_f32_e32 v83, 1.0, v83
	v_rcp_f32_e32 v84, v83
	v_mul_f32_e32 v83, 0xbfb8aa3b, v79
	v_exp_f32_e32 v83, v83
	v_add_f32_e32 v82, 1.0, v82
	v_rcp_f32_e32 v82, v82
	v_add_f32_e32 v83, 1.0, v83
	v_rcp_f32_e32 v83, v83
	s_nop 0
	v_pk_mul_f32 v[78:79], v[78:79], v[82:83]
	s_nop 0
	v_pk_mul_f32 v[70:71], v[70:71], v[78:79]
	v_mul_f32_e32 v78, 0xbfb8aa3b, v75
	v_exp_f32_e32 v78, v78
	s_nop 0
	v_add_f32_e32 v78, 1.0, v78
	v_rcp_f32_e32 v85, v78
	s_nop 0
	v_pk_mul_f32 v[74:75], v[74:75], v[84:85]
	s_nop 0
	v_pk_mul_f32 v[74:75], v[66:67], v[74:75]
	v_mul_f32_e32 v67, 0xbfb8aa3b, v76
	v_exp_f32_e32 v67, v67
	v_mul_f32_e32 v66, 0xbfb8aa3b, v80
	v_exp_f32_e32 v66, v66
	v_add_f32_e32 v67, 1.0, v67
	v_rcp_f32_e32 v78, v67
	v_mul_f32_e32 v67, 0xbfb8aa3b, v81
	v_exp_f32_e32 v67, v67
	v_add_f32_e32 v66, 1.0, v66
	v_rcp_f32_e32 v66, v66
	v_add_f32_e32 v67, 1.0, v67
	v_rcp_f32_e32 v67, v67
	s_nop 0
	v_pk_mul_f32 v[66:67], v[80:81], v[66:67]
	s_nop 0
	v_pk_mul_f32 v[72:73], v[72:73], v[66:67]
	v_mul_f32_e32 v66, 0xbfb8aa3b, v77
	v_exp_f32_e32 v66, v66
	s_nop 0
	v_add_f32_e32 v66, 1.0, v66
	v_rcp_f32_e32 v79, v66
	s_nop 0
	v_pk_mul_f32 v[66:67], v[76:77], v[78:79]
	s_nop 0
	v_pk_mul_f32 v[76:77], v[68:69], v[66:67]
	v_cvt_pk_bf16_f32 v66, v70, v71
	v_cvt_pk_bf16_f32 v67, v72, v73
	v_cvt_pk_bf16_f32 v68, v74, v75
	v_cvt_pk_bf16_f32 v69, v76, v77
	v_mad_i64_i32 v[70:71], s[0:1], v186, s35, v[130:131]
	global_store_dwordx4 v[70:71], v[66:69], off
	s_nop 1
	v_mul_f32_e32 v67, 0xbfb8aa3b, v54
	v_exp_f32_e32 v67, v67
	v_mul_f32_e32 v66, 0xbfb8aa3b, v50
	v_exp_f32_e32 v66, v66
	v_add_f32_e32 v67, 1.0, v67
	v_rcp_f32_e32 v68, v67
	v_mul_f32_e32 v67, 0xbfb8aa3b, v51
	v_exp_f32_e32 v67, v67
	v_add_f32_e32 v66, 1.0, v66
	v_rcp_f32_e32 v66, v66
	v_add_f32_e32 v67, 1.0, v67
	v_rcp_f32_e32 v67, v67
	s_nop 0
	v_pk_mul_f32 v[50:51], v[50:51], v[66:67]
	s_nop 0
	v_pk_mul_f32 v[50:51], v[58:59], v[50:51]
	v_mul_f32_e32 v58, 0xbfb8aa3b, v55
	v_exp_f32_e32 v58, v58
	v_mul_f32_e32 v59, 0xbfb8aa3b, v56
	v_exp_f32_e32 v59, v59
	v_cvt_pk_bf16_f32 v50, v50, v51
	v_add_f32_e32 v58, 1.0, v58
	v_rcp_f32_e32 v69, v58
	v_add_f32_e32 v59, 1.0, v59
	v_mul_f32_e32 v58, 0xbfb8aa3b, v52
	v_exp_f32_e32 v58, v58
	v_pk_mul_f32 v[54:55], v[54:55], v[68:69]
	v_add_f32_e32 v58, 1.0, v58
	v_pk_mul_f32 v[54:55], v[62:63], v[54:55]
	v_rcp_f32_e32 v62, v59
	v_mul_f32_e32 v59, 0xbfb8aa3b, v53
	v_exp_f32_e32 v59, v59
	v_rcp_f32_e32 v58, v58
	v_add_f32_e32 v59, 1.0, v59
	v_rcp_f32_e32 v59, v59
	s_nop 0
	v_pk_mul_f32 v[52:53], v[52:53], v[58:59]
	v_mul_f32_e32 v58, 0xbfb8aa3b, v57
	v_exp_f32_e32 v58, v58
; #define PG8_WAIT_V(n) asm volatile("s_waitcnt vmcnt(" #n ")" ::: "memory")
; #define PG8_BAR __builtin_amdgcn_s_barrier()
; template <class Epi>
; DEVI void gemm_phase(LAS unsigned char* lds, const Gemm g, const Epi& E) {
;     ...
;         if (!has_next) break;
; #pragma unroll
;         for (int a = 0; a < 2; ++a)
; #pragma unroll
;             for (int b = 0; b < 2; ++b)
; #pragma unroll
;                 for (int m = 0; m < 4; ++m)
; #pragma unroll
;                     for (int n = 0; n < 2; ++n) acc[a][b][m][n] = (f32x4){0.f, 0.f, 0.f, 0.f};
;         cur = nxt; cA = nA; cB = nB; ++ui;
;     }
;     PG8_WAIT_V(0);
;     if (wr == 0) PG8_BAR;
;     PG8_BAR;
	v_pk_mul_f32 v[52:53], v[60:61], v[52:53]
	v_add_f32_e32 v58, 1.0, v58
	v_rcp_f32_e32 v63, v58
	v_cvt_pk_bf16_f32 v51, v52, v53
	v_cvt_pk_bf16_f32 v52, v54, v55
	v_mad_i64_i32 v[54:55], s[0:1], v184, s35, v[130:131]
	v_pk_mul_f32 v[56:57], v[56:57], v[62:63]
	s_nop 0
	v_pk_mul_f32 v[56:57], v[64:65], v[56:57]
	s_nop 0
	v_cvt_pk_bf16_f32 v53, v56, v57
	global_store_dwordx4 v[54:55], v[50:53], off
	s_nop 1
	v_mul_f32_e32 v51, 0xbfb8aa3b, v38
	v_exp_f32_e32 v51, v51
	v_mul_f32_e32 v50, 0xbfb8aa3b, v34
	v_exp_f32_e32 v50, v50
	v_add_f32_e32 v51, 1.0, v51
	v_rcp_f32_e32 v52, v51
	v_mul_f32_e32 v51, 0xbfb8aa3b, v35
	v_exp_f32_e32 v51, v51
	v_add_f32_e32 v50, 1.0, v50
	v_rcp_f32_e32 v50, v50
	v_add_f32_e32 v51, 1.0, v51
	v_rcp_f32_e32 v51, v51
	s_nop 0
	v_pk_mul_f32 v[34:35], v[34:35], v[50:51]
	s_nop 0
	v_pk_mul_f32 v[34:35], v[42:43], v[34:35]
	v_mul_f32_e32 v42, 0xbfb8aa3b, v39
	v_exp_f32_e32 v42, v42
	v_mul_f32_e32 v43, 0xbfb8aa3b, v40
	v_exp_f32_e32 v43, v43
	v_cvt_pk_bf16_f32 v34, v34, v35
	v_add_f32_e32 v42, 1.0, v42
	v_rcp_f32_e32 v53, v42
	v_add_f32_e32 v43, 1.0, v43
	v_mul_f32_e32 v42, 0xbfb8aa3b, v36
	v_exp_f32_e32 v42, v42
	v_pk_mul_f32 v[38:39], v[38:39], v[52:53]
	v_add_f32_e32 v42, 1.0, v42
	v_pk_mul_f32 v[38:39], v[46:47], v[38:39]
	v_rcp_f32_e32 v46, v43
	v_mul_f32_e32 v43, 0xbfb8aa3b, v37
	v_exp_f32_e32 v43, v43
	v_rcp_f32_e32 v42, v42
	v_add_f32_e32 v43, 1.0, v43
	v_rcp_f32_e32 v43, v43
	s_nop 0
	v_pk_mul_f32 v[36:37], v[36:37], v[42:43]
	v_mul_f32_e32 v42, 0xbfb8aa3b, v41
	v_exp_f32_e32 v42, v42
	v_pk_mul_f32 v[36:37], v[44:45], v[36:37]
	v_add_f32_e32 v42, 1.0, v42
	v_rcp_f32_e32 v47, v42
	v_cvt_pk_bf16_f32 v35, v36, v37
	v_cvt_pk_bf16_f32 v36, v38, v39
	v_mad_i64_i32 v[38:39], s[0:1], v182, s35, v[130:131]
	v_pk_mul_f32 v[40:41], v[40:41], v[46:47]
	s_nop 0
	v_pk_mul_f32 v[40:41], v[48:49], v[40:41]
	s_nop 0
	v_cvt_pk_bf16_f32 v37, v40, v41
	global_store_dwordx4 v[38:39], v[34:37], off
	s_nop 1
	v_mul_f32_e32 v35, 0xbfb8aa3b, v22
	v_exp_f32_e32 v35, v35
	v_mul_f32_e32 v34, 0xbfb8aa3b, v18
	v_exp_f32_e32 v34, v34
	v_add_f32_e32 v35, 1.0, v35
	v_rcp_f32_e32 v36, v35
	v_mul_f32_e32 v35, 0xbfb8aa3b, v19
	v_exp_f32_e32 v35, v35
	v_add_f32_e32 v34, 1.0, v34
	v_rcp_f32_e32 v34, v34
	v_add_f32_e32 v35, 1.0, v35
	v_rcp_f32_e32 v35, v35
	s_nop 0
	v_pk_mul_f32 v[18:19], v[18:19], v[34:35]
	s_nop 0
	v_pk_mul_f32 v[18:19], v[26:27], v[18:19]
	v_mul_f32_e32 v26, 0xbfb8aa3b, v23
	v_exp_f32_e32 v26, v26
	v_mul_f32_e32 v27, 0xbfb8aa3b, v24
	v_exp_f32_e32 v27, v27
	v_cvt_pk_bf16_f32 v18, v18, v19
	v_add_f32_e32 v26, 1.0, v26
	v_rcp_f32_e32 v37, v26
	v_add_f32_e32 v27, 1.0, v27
	v_mul_f32_e32 v26, 0xbfb8aa3b, v20
	v_exp_f32_e32 v26, v26
	v_pk_mul_f32 v[22:23], v[22:23], v[36:37]
	v_add_f32_e32 v26, 1.0, v26
	v_pk_mul_f32 v[22:23], v[30:31], v[22:23]
	v_rcp_f32_e32 v30, v27
	v_mul_f32_e32 v27, 0xbfb8aa3b, v21
	v_exp_f32_e32 v27, v27
	v_rcp_f32_e32 v26, v26
	v_add_f32_e32 v27, 1.0, v27
	v_rcp_f32_e32 v27, v27
	s_nop 0
	v_pk_mul_f32 v[20:21], v[20:21], v[26:27]
	v_mul_f32_e32 v26, 0xbfb8aa3b, v25
	v_exp_f32_e32 v26, v26
	v_pk_mul_f32 v[20:21], v[28:29], v[20:21]
	v_add_f32_e32 v26, 1.0, v26
	v_rcp_f32_e32 v31, v26
	v_cvt_pk_bf16_f32 v19, v20, v21
	v_cvt_pk_bf16_f32 v20, v22, v23
	v_mad_i64_i32 v[22:23], s[0:1], v180, s35, v[130:131]
	v_pk_mul_f32 v[24:25], v[24:25], v[30:31]
	s_nop 0
	v_pk_mul_f32 v[24:25], v[32:33], v[24:25]
	s_nop 0
	v_cvt_pk_bf16_f32 v21, v24, v25
	global_store_dwordx4 v[22:23], v[18:21], off
	s_nop 1
	v_mul_f32_e32 v19, 0xbfb8aa3b, v4
	v_exp_f32_e32 v19, v19
	v_mul_f32_e32 v18, 0xbfb8aa3b, v0
	v_exp_f32_e32 v18, v18
	v_add_f32_e32 v19, 1.0, v19
	v_rcp_f32_e32 v20, v19
	v_mul_f32_e32 v19, 0xbfb8aa3b, v1
	v_exp_f32_e32 v19, v19
	v_add_f32_e32 v18, 1.0, v18
	v_rcp_f32_e32 v18, v18
	v_add_f32_e32 v19, 1.0, v19
	v_rcp_f32_e32 v19, v19
	s_nop 0
	v_pk_mul_f32 v[0:1], v[0:1], v[18:19]
	s_nop 0
	v_pk_mul_f32 v[0:1], v[10:11], v[0:1]
	v_mul_f32_e32 v10, 0xbfb8aa3b, v5
	v_exp_f32_e32 v10, v10
	v_mul_f32_e32 v11, 0xbfb8aa3b, v6
	v_exp_f32_e32 v11, v11
	v_cvt_pk_bf16_f32 v0, v0, v1
	v_add_f32_e32 v10, 1.0, v10
	v_rcp_f32_e32 v21, v10
	v_add_f32_e32 v11, 1.0, v11
	v_mul_f32_e32 v10, 0xbfb8aa3b, v2
	v_exp_f32_e32 v10, v10
	v_pk_mul_f32 v[4:5], v[4:5], v[20:21]
	v_add_f32_e32 v10, 1.0, v10
	v_pk_mul_f32 v[4:5], v[14:15], v[4:5]
	v_rcp_f32_e32 v14, v11
	v_mul_f32_e32 v11, 0xbfb8aa3b, v3
	v_exp_f32_e32 v11, v11
	v_rcp_f32_e32 v10, v10
	v_add_f32_e32 v11, 1.0, v11
	v_rcp_f32_e32 v11, v11
	s_nop 0
	v_pk_mul_f32 v[2:3], v[2:3], v[10:11]
	v_mul_f32_e32 v10, 0xbfb8aa3b, v7
	v_exp_f32_e32 v10, v10
	v_pk_mul_f32 v[2:3], v[12:13], v[2:3]
	v_add_f32_e32 v10, 1.0, v10
	v_rcp_f32_e32 v15, v10
	v_cvt_pk_bf16_f32 v1, v2, v3
	v_cvt_pk_bf16_f32 v2, v4, v5
	v_mad_i64_i32 v[4:5], s[0:1], v178, s35, v[130:131]
	v_pk_mul_f32 v[6:7], v[6:7], v[14:15]
	s_nop 0
	v_pk_mul_f32 v[6:7], v[16:17], v[6:7]
	s_nop 0
	v_cvt_pk_bf16_f32 v3, v6, v7
	global_store_dwordx4 v[4:5], v[0:3], off
	s_cbranch_vccz .LBB0_1669
	s_waitcnt vmcnt(0)
	s_cmpk_gt_u32 s66, 0xff
	s_cbranch_scc1 .LBB0_1676
	s_barrier
